# G6 + s_setprio 1/0 around each 32-MFMA segment restored
# baseline (speedup 1.0000x reference)
.LBB0_200:
	ds_read_b128 v[148:151], v169
	ds_read_b128 v[152:155], v169 offset:1024
	ds_read_b128 v[156:159], v169 offset:2048
	ds_read_b128 v[160:163], v169 offset:3072
	ds_read_b128 v[174:177], v170
	ds_read_b128 v[178:181], v170 offset:1024
	ds_read_b128 v[182:185], v170 offset:2048
	ds_read_b128 v[186:189], v170 offset:3072
	s_add_u32 s26, s6, 0xfff00800
	s_addc_u32 s27, s7, -1
	s_cmp_eq_u32 s34, 60
	s_cselect_b32 s29, s17, s27
	s_cselect_b32 s28, s23, s26
	s_cselect_b32 s27, s15, s31
	s_cselect_b32 s26, s25, s30
	v_lshl_add_u64 v[190:191], s[6:7], 0, v[138:139]
	s_add_i32 m0, s41, 0xc000
	s_nop 0
	global_load_lds_dwordx4 v[190:191], off
	v_lshl_add_u64 v[190:191], s[6:7], 0, v[140:141]
	s_add_i32 m0, s41, 0xe000
	s_nop 0
	global_load_lds_dwordx4 v[190:191], off
	ds_read_b128 v[190:193], v171
	ds_read_b128 v[194:197], v171 offset:1024
	ds_read_b128 v[198:201], v171 offset:2048
	ds_read_b128 v[202:205], v171 offset:3072
	ds_read_b128 v[206:209], v171 offset:4096
	ds_read_b128 v[210:213], v171 offset:5120
	ds_read_b128 v[214:217], v171 offset:6144
	ds_read_b128 v[218:221], v171 offset:7168
	s_waitcnt vmcnt(8)
	s_waitcnt lgkmcnt(0)
	s_barrier
	s_waitcnt lgkmcnt(0)
	s_setprio 1
	v_mfma_f32_16x16x32_bf16 v[124:127], v[148:151], v[190:193], v[124:127]
	v_mfma_f32_16x16x32_bf16 v[124:127], v[152:155], v[194:197], v[124:127]
	v_mfma_f32_16x16x32_bf16 v[120:123], v[160:163], v[194:197], v[120:123]
	v_mfma_f32_16x16x32_bf16 v[120:123], v[156:159], v[190:193], v[120:123]
	v_mfma_f32_16x16x32_bf16 v[60:63], v[174:177], v[190:193], v[60:63]
	v_mfma_f32_16x16x32_bf16 v[60:63], v[178:181], v[194:197], v[60:63]
	v_mfma_f32_16x16x32_bf16 v[56:59], v[186:189], v[194:197], v[56:59]
	v_mfma_f32_16x16x32_bf16 v[56:59], v[182:185], v[190:193], v[56:59]
	v_mfma_f32_16x16x32_bf16 v[48:51], v[182:185], v[198:201], v[48:51]
	v_mfma_f32_16x16x32_bf16 v[48:51], v[186:189], v[202:205], v[48:51]
	v_mfma_f32_16x16x32_bf16 v[52:55], v[178:181], v[202:205], v[52:55]
	v_mfma_f32_16x16x32_bf16 v[52:55], v[174:177], v[198:201], v[52:55]
	v_mfma_f32_16x16x32_bf16 v[112:115], v[156:159], v[198:201], v[112:115]
	v_mfma_f32_16x16x32_bf16 v[112:115], v[160:163], v[202:205], v[112:115]
	v_mfma_f32_16x16x32_bf16 v[116:119], v[152:155], v[202:205], v[116:119]
	v_mfma_f32_16x16x32_bf16 v[116:119], v[148:151], v[198:201], v[116:119]
	v_mfma_f32_16x16x32_bf16 v[108:111], v[148:151], v[206:209], v[108:111]
	v_mfma_f32_16x16x32_bf16 v[108:111], v[152:155], v[210:213], v[108:111]
	v_mfma_f32_16x16x32_bf16 v[104:107], v[160:163], v[210:213], v[104:107]
	v_mfma_f32_16x16x32_bf16 v[104:107], v[156:159], v[206:209], v[104:107]
	v_mfma_f32_16x16x32_bf16 v[44:47], v[174:177], v[206:209], v[44:47]
	v_mfma_f32_16x16x32_bf16 v[44:47], v[178:181], v[210:213], v[44:47]
	v_mfma_f32_16x16x32_bf16 v[40:43], v[186:189], v[210:213], v[40:43]
	v_mfma_f32_16x16x32_bf16 v[40:43], v[182:185], v[206:209], v[40:43]
	v_mfma_f32_16x16x32_bf16 v[32:35], v[182:185], v[214:217], v[32:35]
	v_mfma_f32_16x16x32_bf16 v[32:35], v[186:189], v[218:221], v[32:35]
	v_mfma_f32_16x16x32_bf16 v[36:39], v[178:181], v[218:221], v[36:39]
	v_mfma_f32_16x16x32_bf16 v[36:39], v[174:177], v[214:217], v[36:39]
	v_mfma_f32_16x16x32_bf16 v[96:99], v[156:159], v[214:217], v[96:99]
	v_mfma_f32_16x16x32_bf16 v[96:99], v[160:163], v[218:221], v[96:99]
	v_mfma_f32_16x16x32_bf16 v[100:103], v[152:155], v[218:221], v[100:103]
	v_mfma_f32_16x16x32_bf16 v[100:103], v[148:151], v[214:217], v[100:103]
	s_setprio 0
	s_barrier
	s_add_i32 s35, s55, s36
	v_lshl_add_u64 v[222:223], s[26:27], 0, v[130:131]
	s_mov_b32 m0, s35
	v_lshl_add_u64 v[224:225], s[26:27], 0, v[134:135]
	global_load_lds_dwordx4 v[222:223], off
	s_add_i32 m0, s35, 0x2000
	s_add_u32 s58, s26, 0x100000
	s_addc_u32 s59, s27, 0
	s_add_i32 s35, s56, s36
	global_load_lds_dwordx4 v[224:225], off
	v_lshl_add_u64 v[190:191], s[58:59], 0, v[130:131]
	s_mov_b32 m0, s35
	v_lshl_add_u64 v[226:227], s[28:29], 0, v[128:129]
	global_load_lds_dwordx4 v[190:191], off
	v_lshl_add_u64 v[190:191], s[58:59], 0, v[134:135]
	s_add_i32 m0, s35, 0x2000
	v_lshl_add_u64 v[228:229], s[28:29], 0, v[132:133]
	global_load_lds_dwordx4 v[190:191], off
	s_mov_b32 m0, s41
	s_nop 0
	global_load_lds_dwordx4 v[226:227], off
	s_mov_b32 m0, s42
	s_nop 0
	global_load_lds_dwordx4 v[228:229], off
	ds_read_b128 v[190:193], v171 offset:16384
	ds_read_b128 v[194:197], v171 offset:17408
	ds_read_b128 v[198:201], v171 offset:18432
	ds_read_b128 v[202:205], v171 offset:19456
	ds_read_b128 v[206:209], v171 offset:20480
	ds_read_b128 v[210:213], v171 offset:21504
	ds_read_b128 v[214:217], v171 offset:22528
	ds_read_b128 v[218:221], v171 offset:23552
	s_waitcnt vmcnt(8)
	s_waitcnt lgkmcnt(0)
	s_barrier
	s_waitcnt lgkmcnt(0)
	s_setprio 1
	v_mfma_f32_16x16x32_bf16 v[92:95], v[148:151], v[190:193], v[92:95]
	v_mfma_f32_16x16x32_bf16 v[92:95], v[152:155], v[194:197], v[92:95]
	v_mfma_f32_16x16x32_bf16 v[88:91], v[160:163], v[194:197], v[88:91]
	v_mfma_f32_16x16x32_bf16 v[88:91], v[156:159], v[190:193], v[88:91]
	v_mfma_f32_16x16x32_bf16 v[28:31], v[174:177], v[190:193], v[28:31]
	v_mfma_f32_16x16x32_bf16 v[28:31], v[178:181], v[194:197], v[28:31]
	v_mfma_f32_16x16x32_bf16 v[24:27], v[186:189], v[194:197], v[24:27]
	v_mfma_f32_16x16x32_bf16 v[24:27], v[182:185], v[190:193], v[24:27]
	v_mfma_f32_16x16x32_bf16 v[16:19], v[182:185], v[198:201], v[16:19]
	v_mfma_f32_16x16x32_bf16 v[16:19], v[186:189], v[202:205], v[16:19]
	v_mfma_f32_16x16x32_bf16 v[20:23], v[178:181], v[202:205], v[20:23]
	v_mfma_f32_16x16x32_bf16 v[20:23], v[174:177], v[198:201], v[20:23]
	v_mfma_f32_16x16x32_bf16 v[80:83], v[156:159], v[198:201], v[80:83]
	v_mfma_f32_16x16x32_bf16 v[80:83], v[160:163], v[202:205], v[80:83]
	v_mfma_f32_16x16x32_bf16 v[84:87], v[152:155], v[202:205], v[84:87]
	v_mfma_f32_16x16x32_bf16 v[84:87], v[148:151], v[198:201], v[84:87]
	v_mfma_f32_16x16x32_bf16 v[76:79], v[148:151], v[206:209], v[76:79]
	v_mfma_f32_16x16x32_bf16 v[76:79], v[152:155], v[210:213], v[76:79]
	v_mfma_f32_16x16x32_bf16 v[72:75], v[160:163], v[210:213], v[72:75]
	v_mfma_f32_16x16x32_bf16 v[72:75], v[156:159], v[206:209], v[72:75]
	v_mfma_f32_16x16x32_bf16 v[12:15], v[174:177], v[206:209], v[12:15]
	v_mfma_f32_16x16x32_bf16 v[12:15], v[178:181], v[210:213], v[12:15]
	v_mfma_f32_16x16x32_bf16 v[8:11], v[186:189], v[210:213], v[8:11]
	v_mfma_f32_16x16x32_bf16 v[8:11], v[182:185], v[206:209], v[8:11]
	v_mfma_f32_16x16x32_bf16 v[0:3], v[182:185], v[214:217], v[0:3]
	v_mfma_f32_16x16x32_bf16 v[0:3], v[186:189], v[218:221], v[0:3]
	v_mfma_f32_16x16x32_bf16 v[4:7], v[178:181], v[218:221], v[4:7]
	v_mfma_f32_16x16x32_bf16 v[4:7], v[174:177], v[214:217], v[4:7]
	v_mfma_f32_16x16x32_bf16 v[64:67], v[156:159], v[214:217], v[64:67]
	v_mfma_f32_16x16x32_bf16 v[64:67], v[160:163], v[218:221], v[64:67]
	v_mfma_f32_16x16x32_bf16 v[68:71], v[152:155], v[218:221], v[68:71]
	v_mfma_f32_16x16x32_bf16 v[68:71], v[148:151], v[214:217], v[68:71]
	s_setprio 0
	s_barrier
	s_add_i32 s35, 0, 0x18000
	v_add_u32_e32 v136, s35, v165
	s_add_i32 s57, 0, 0x1c000
	ds_read_b128 v[148:151], v136
	ds_read_b128 v[152:155], v136 offset:1024
	ds_read_b128 v[156:159], v136 offset:2048
	ds_read_b128 v[160:163], v136 offset:3072
	v_add_u32_e32 v136, s57, v165
	ds_read_b128 v[174:177], v136
	ds_read_b128 v[178:181], v136 offset:1024
	ds_read_b128 v[182:185], v136 offset:2048
	ds_read_b128 v[186:189], v136 offset:3072
	s_add_u32 s28, s28, 0x100000
	s_addc_u32 s29, s29, 0
	s_mov_b32 m0, s43
	v_lshl_add_u64 v[190:191], s[28:29], 0, v[128:129]
	global_load_lds_dwordx4 v[190:191], off
	v_lshl_add_u64 v[190:191], s[28:29], 0, v[132:133]
	s_mov_b32 m0, s44
	s_nop 0
	global_load_lds_dwordx4 v[190:191], off
	ds_read_b128 v[190:193], v171 offset:32768
	ds_read_b128 v[194:197], v171 offset:33792
	ds_read_b128 v[198:201], v171 offset:34816
	ds_read_b128 v[202:205], v171 offset:35840
	ds_read_b128 v[206:209], v171 offset:36864
	ds_read_b128 v[210:213], v171 offset:37888
	ds_read_b128 v[214:217], v171 offset:38912
	ds_read_b128 v[218:221], v171 offset:39936
	s_waitcnt vmcnt(8)
	s_waitcnt lgkmcnt(0)
	s_barrier
	s_waitcnt lgkmcnt(0)
	s_setprio 1
	v_mfma_f32_16x16x32_bf16 v[124:127], v[148:151], v[190:193], v[124:127]
	v_mfma_f32_16x16x32_bf16 v[124:127], v[152:155], v[194:197], v[124:127]
	v_mfma_f32_16x16x32_bf16 v[120:123], v[160:163], v[194:197], v[120:123]
	v_mfma_f32_16x16x32_bf16 v[120:123], v[156:159], v[190:193], v[120:123]
	v_mfma_f32_16x16x32_bf16 v[60:63], v[174:177], v[190:193], v[60:63]
	v_mfma_f32_16x16x32_bf16 v[60:63], v[178:181], v[194:197], v[60:63]
	v_mfma_f32_16x16x32_bf16 v[56:59], v[186:189], v[194:197], v[56:59]
	v_mfma_f32_16x16x32_bf16 v[56:59], v[182:185], v[190:193], v[56:59]
	v_mfma_f32_16x16x32_bf16 v[48:51], v[182:185], v[198:201], v[48:51]
	v_mfma_f32_16x16x32_bf16 v[48:51], v[186:189], v[202:205], v[48:51]
	v_mfma_f32_16x16x32_bf16 v[52:55], v[178:181], v[202:205], v[52:55]
	v_mfma_f32_16x16x32_bf16 v[52:55], v[174:177], v[198:201], v[52:55]
	v_mfma_f32_16x16x32_bf16 v[112:115], v[156:159], v[198:201], v[112:115]
	v_mfma_f32_16x16x32_bf16 v[112:115], v[160:163], v[202:205], v[112:115]
	v_mfma_f32_16x16x32_bf16 v[116:119], v[152:155], v[202:205], v[116:119]
	v_mfma_f32_16x16x32_bf16 v[116:119], v[148:151], v[198:201], v[116:119]
	v_mfma_f32_16x16x32_bf16 v[108:111], v[148:151], v[206:209], v[108:111]
	v_mfma_f32_16x16x32_bf16 v[108:111], v[152:155], v[210:213], v[108:111]
	v_mfma_f32_16x16x32_bf16 v[104:107], v[160:163], v[210:213], v[104:107]
	v_mfma_f32_16x16x32_bf16 v[104:107], v[156:159], v[206:209], v[104:107]
	v_mfma_f32_16x16x32_bf16 v[44:47], v[174:177], v[206:209], v[44:47]
	v_mfma_f32_16x16x32_bf16 v[44:47], v[178:181], v[210:213], v[44:47]
	v_mfma_f32_16x16x32_bf16 v[40:43], v[186:189], v[210:213], v[40:43]
	v_mfma_f32_16x16x32_bf16 v[40:43], v[182:185], v[206:209], v[40:43]
	v_mfma_f32_16x16x32_bf16 v[32:35], v[182:185], v[214:217], v[32:35]
	v_mfma_f32_16x16x32_bf16 v[32:35], v[186:189], v[218:221], v[32:35]
	v_mfma_f32_16x16x32_bf16 v[36:39], v[178:181], v[218:221], v[36:39]
	v_mfma_f32_16x16x32_bf16 v[36:39], v[174:177], v[214:217], v[36:39]
	v_mfma_f32_16x16x32_bf16 v[96:99], v[156:159], v[214:217], v[96:99]
	v_mfma_f32_16x16x32_bf16 v[96:99], v[160:163], v[218:221], v[96:99]
	v_mfma_f32_16x16x32_bf16 v[100:103], v[152:155], v[218:221], v[100:103]
	v_mfma_f32_16x16x32_bf16 v[100:103], v[148:151], v[214:217], v[100:103]
	s_setprio 0
	s_barrier
	s_add_i32 s28, s35, s36
	v_lshl_add_u64 v[190:191], v[222:223], 0, s[12:13]
	s_mov_b32 m0, s28
	s_nop 0
	global_load_lds_dwordx4 v[190:191], off
	s_add_i32 m0, s28, 0x2000
	s_add_u32 s26, s26, 0x100800
	v_lshl_add_u64 v[190:191], v[224:225], 0, s[12:13]
	s_addc_u32 s27, s27, 0
	s_add_i32 s28, s57, s36
	global_load_lds_dwordx4 v[190:191], off
	v_lshl_add_u64 v[190:191], s[26:27], 0, v[130:131]
	s_mov_b32 m0, s28
	s_nop 0
	global_load_lds_dwordx4 v[190:191], off
	v_lshl_add_u64 v[190:191], s[26:27], 0, v[134:135]
	s_add_i32 m0, s28, 0x2000
	s_nop 0
	global_load_lds_dwordx4 v[190:191], off
	v_lshl_add_u64 v[190:191], v[226:227], 0, s[12:13]
	s_mov_b32 m0, s49
	s_nop 0
	global_load_lds_dwordx4 v[190:191], off
	v_lshl_add_u64 v[190:191], v[228:229], 0, s[12:13]
	s_mov_b32 m0, s50
	s_nop 0
	global_load_lds_dwordx4 v[190:191], off
	ds_read_b128 v[190:193], v171 offset:49152
	ds_read_b128 v[194:197], v171 offset:50176
	ds_read_b128 v[198:201], v171 offset:51200
	ds_read_b128 v[202:205], v171 offset:52224
	ds_read_b128 v[206:209], v171 offset:53248
	ds_read_b128 v[210:213], v171 offset:54272
	ds_read_b128 v[214:217], v171 offset:55296
	ds_read_b128 v[218:221], v171 offset:56320
	s_waitcnt vmcnt(8)
	s_waitcnt lgkmcnt(0)
	s_barrier
	s_waitcnt lgkmcnt(0)
	s_setprio 1
	v_mfma_f32_16x16x32_bf16 v[92:95], v[148:151], v[190:193], v[92:95]
	v_mfma_f32_16x16x32_bf16 v[92:95], v[152:155], v[194:197], v[92:95]
	v_mfma_f32_16x16x32_bf16 v[88:91], v[160:163], v[194:197], v[88:91]
	v_mfma_f32_16x16x32_bf16 v[88:91], v[156:159], v[190:193], v[88:91]
	v_mfma_f32_16x16x32_bf16 v[28:31], v[174:177], v[190:193], v[28:31]
	v_mfma_f32_16x16x32_bf16 v[28:31], v[178:181], v[194:197], v[28:31]
	v_mfma_f32_16x16x32_bf16 v[24:27], v[186:189], v[194:197], v[24:27]
	v_mfma_f32_16x16x32_bf16 v[24:27], v[182:185], v[190:193], v[24:27]
	v_mfma_f32_16x16x32_bf16 v[16:19], v[182:185], v[198:201], v[16:19]
	v_mfma_f32_16x16x32_bf16 v[16:19], v[186:189], v[202:205], v[16:19]
	v_mfma_f32_16x16x32_bf16 v[20:23], v[178:181], v[202:205], v[20:23]
	v_mfma_f32_16x16x32_bf16 v[20:23], v[174:177], v[198:201], v[20:23]
	v_mfma_f32_16x16x32_bf16 v[80:83], v[156:159], v[198:201], v[80:83]
	v_mfma_f32_16x16x32_bf16 v[80:83], v[160:163], v[202:205], v[80:83]
	v_mfma_f32_16x16x32_bf16 v[84:87], v[152:155], v[202:205], v[84:87]
	v_mfma_f32_16x16x32_bf16 v[84:87], v[148:151], v[198:201], v[84:87]
	v_mfma_f32_16x16x32_bf16 v[76:79], v[148:151], v[206:209], v[76:79]
	v_mfma_f32_16x16x32_bf16 v[76:79], v[152:155], v[210:213], v[76:79]
	v_mfma_f32_16x16x32_bf16 v[72:75], v[160:163], v[210:213], v[72:75]
	v_mfma_f32_16x16x32_bf16 v[72:75], v[156:159], v[206:209], v[72:75]
	v_mfma_f32_16x16x32_bf16 v[12:15], v[174:177], v[206:209], v[12:15]
	v_mfma_f32_16x16x32_bf16 v[12:15], v[178:181], v[210:213], v[12:15]
	v_mfma_f32_16x16x32_bf16 v[8:11], v[186:189], v[210:213], v[8:11]
	v_mfma_f32_16x16x32_bf16 v[8:11], v[182:185], v[206:209], v[8:11]
	v_mfma_f32_16x16x32_bf16 v[0:3], v[182:185], v[214:217], v[0:3]
	v_mfma_f32_16x16x32_bf16 v[0:3], v[186:189], v[218:221], v[0:3]
	v_mfma_f32_16x16x32_bf16 v[4:7], v[178:181], v[218:221], v[4:7]
	v_mfma_f32_16x16x32_bf16 v[4:7], v[174:177], v[214:217], v[4:7]
	v_mfma_f32_16x16x32_bf16 v[64:67], v[156:159], v[214:217], v[64:67]
	v_mfma_f32_16x16x32_bf16 v[64:67], v[160:163], v[218:221], v[64:67]
	v_mfma_f32_16x16x32_bf16 v[68:71], v[152:155], v[218:221], v[68:71]
	v_mfma_f32_16x16x32_bf16 v[68:71], v[148:151], v[214:217], v[68:71]
	s_setprio 0
	s_barrier
	s_add_i32 s34, s34, 2
	s_add_u32 s6, s6, 0x1000
	s_addc_u32 s7, s7, 0
	s_add_u32 s30, s30, 0x1000
	s_addc_u32 s31, s31, 0
	s_cmp_gt_u32 s34, 61
	s_cbranch_scc0 .LBB0_200
	s_and_b64 vcc, exec, s[0:1]
	s_cbranch_vccz .LBB0_203
	s_barrier

.LBB0_333:
	ds_read_b128 v[144:147], v152
	ds_read_b128 v[156:159], v152 offset:1024
	ds_read_b128 v[160:163], v152 offset:2048
	ds_read_b128 v[164:167], v152 offset:3072
	ds_read_b128 v[168:171], v153
	ds_read_b128 v[172:175], v153 offset:1024
	ds_read_b128 v[176:179], v153 offset:2048
	ds_read_b128 v[180:183], v153 offset:3072
	s_add_u32 s28, s24, 0x100
	s_addc_u32 s29, s25, 0
	s_cmp_eq_u32 s56, 60
	s_cselect_b32 s35, s13, s29
	s_cselect_b32 s34, s52, s28
	s_cselect_b32 s31, s11, s55
	s_cselect_b32 s30, s53, s54
	v_lshl_add_u64 v[184:185], s[24:25], 0, v[136:137]
	s_add_i32 m0, s21, 0xc000
	s_nop 0
	global_load_lds_dwordx4 v[184:185], off
	v_lshl_add_u64 v[184:185], s[24:25], 0, v[138:139]
	s_add_i32 m0, s21, 0xe000
	s_nop 0
	global_load_lds_dwordx4 v[184:185], off
	ds_read_b128 v[184:187], v154
	ds_read_b128 v[188:191], v154 offset:1024
	ds_read_b128 v[192:195], v154 offset:2048
	ds_read_b128 v[196:199], v154 offset:3072
	ds_read_b128 v[200:203], v154 offset:4096
	ds_read_b128 v[204:207], v154 offset:5120
	ds_read_b128 v[208:211], v154 offset:6144
	ds_read_b128 v[212:215], v154 offset:7168
	s_waitcnt vmcnt(8)
	s_waitcnt lgkmcnt(0)
	s_barrier
	s_waitcnt lgkmcnt(0)
	s_setprio 1
	v_mfma_f32_16x16x32_bf16 v[124:127], v[144:147], v[184:187], v[124:127]
	v_mfma_f32_16x16x32_bf16 v[124:127], v[156:159], v[188:191], v[124:127]
	v_mfma_f32_16x16x32_bf16 v[120:123], v[164:167], v[188:191], v[120:123]
	v_mfma_f32_16x16x32_bf16 v[120:123], v[160:163], v[184:187], v[120:123]
	v_mfma_f32_16x16x32_bf16 v[112:115], v[168:171], v[184:187], v[112:115]
	v_mfma_f32_16x16x32_bf16 v[112:115], v[172:175], v[188:191], v[112:115]
	v_mfma_f32_16x16x32_bf16 v[104:107], v[180:183], v[188:191], v[104:107]
	v_mfma_f32_16x16x32_bf16 v[104:107], v[176:179], v[184:187], v[104:107]
	v_mfma_f32_16x16x32_bf16 v[88:91], v[176:179], v[192:195], v[88:91]
	v_mfma_f32_16x16x32_bf16 v[88:91], v[180:183], v[196:199], v[88:91]
	v_mfma_f32_16x16x32_bf16 v[96:99], v[172:175], v[196:199], v[96:99]
	v_mfma_f32_16x16x32_bf16 v[96:99], v[168:171], v[192:195], v[96:99]
	v_mfma_f32_16x16x32_bf16 v[108:111], v[160:163], v[192:195], v[108:111]
	v_mfma_f32_16x16x32_bf16 v[108:111], v[164:167], v[196:199], v[108:111]
	v_mfma_f32_16x16x32_bf16 v[116:119], v[156:159], v[196:199], v[116:119]
	v_mfma_f32_16x16x32_bf16 v[116:119], v[144:147], v[192:195], v[116:119]
	v_mfma_f32_16x16x32_bf16 v[100:103], v[144:147], v[200:203], v[100:103]
	v_mfma_f32_16x16x32_bf16 v[100:103], v[156:159], v[204:207], v[100:103]
	v_mfma_f32_16x16x32_bf16 v[92:95], v[164:167], v[204:207], v[92:95]
	v_mfma_f32_16x16x32_bf16 v[92:95], v[160:163], v[200:203], v[92:95]
	v_mfma_f32_16x16x32_bf16 v[80:83], v[168:171], v[200:203], v[80:83]
	v_mfma_f32_16x16x32_bf16 v[80:83], v[172:175], v[204:207], v[80:83]
	v_mfma_f32_16x16x32_bf16 v[72:75], v[180:183], v[204:207], v[72:75]
	v_mfma_f32_16x16x32_bf16 v[72:75], v[176:179], v[200:203], v[72:75]
	v_mfma_f32_16x16x32_bf16 v[64:67], v[176:179], v[208:211], v[64:67]
	v_mfma_f32_16x16x32_bf16 v[64:67], v[180:183], v[212:215], v[64:67]
	v_mfma_f32_16x16x32_bf16 v[68:71], v[172:175], v[212:215], v[68:71]
	v_mfma_f32_16x16x32_bf16 v[68:71], v[168:171], v[208:211], v[68:71]
	v_mfma_f32_16x16x32_bf16 v[76:79], v[160:163], v[208:211], v[76:79]
	v_mfma_f32_16x16x32_bf16 v[76:79], v[164:167], v[212:215], v[76:79]
	v_mfma_f32_16x16x32_bf16 v[84:87], v[156:159], v[212:215], v[84:87]
	v_mfma_f32_16x16x32_bf16 v[84:87], v[144:147], v[208:211], v[84:87]
	s_setprio 0
	s_barrier
	s_add_i32 s24, s49, s41
	v_lshl_add_u64 v[216:217], s[30:31], 0, v[130:131]
	s_mov_b32 m0, s24
	v_lshl_add_u64 v[218:219], s[30:31], 0, v[134:135]
	global_load_lds_dwordx4 v[216:217], off
	s_add_i32 m0, s24, 0x2000
	s_add_u32 s24, s30, 0x100000
	s_addc_u32 s25, s31, 0
	s_add_i32 s57, s50, s41
	global_load_lds_dwordx4 v[218:219], off
	v_lshl_add_u64 v[184:185], s[24:25], 0, v[130:131]
	s_mov_b32 m0, s57
	v_lshl_add_u64 v[220:221], s[34:35], 0, v[128:129]
	global_load_lds_dwordx4 v[184:185], off
	v_lshl_add_u64 v[184:185], s[24:25], 0, v[134:135]
	s_add_i32 m0, s57, 0x2000
	v_lshl_add_u64 v[222:223], s[34:35], 0, v[132:133]
	global_load_lds_dwordx4 v[184:185], off
	s_mov_b32 m0, s21
	s_nop 0
	global_load_lds_dwordx4 v[220:221], off
	s_mov_b32 m0, s42
	s_nop 0
	global_load_lds_dwordx4 v[222:223], off
	ds_read_b128 v[184:187], v154 offset:16384
	ds_read_b128 v[188:191], v154 offset:17408
	ds_read_b128 v[192:195], v154 offset:18432
	ds_read_b128 v[196:199], v154 offset:19456
	ds_read_b128 v[200:203], v154 offset:20480
	ds_read_b128 v[204:207], v154 offset:21504
	ds_read_b128 v[208:211], v154 offset:22528
	ds_read_b128 v[212:215], v154 offset:23552
	s_waitcnt vmcnt(8)
	s_waitcnt lgkmcnt(0)
	s_barrier
	s_waitcnt lgkmcnt(0)
	s_setprio 1
	v_mfma_f32_16x16x32_bf16 v[60:63], v[144:147], v[184:187], v[60:63]
	v_mfma_f32_16x16x32_bf16 v[60:63], v[156:159], v[188:191], v[60:63]
	v_mfma_f32_16x16x32_bf16 v[56:59], v[164:167], v[188:191], v[56:59]
	v_mfma_f32_16x16x32_bf16 v[56:59], v[160:163], v[184:187], v[56:59]
	v_mfma_f32_16x16x32_bf16 v[48:51], v[168:171], v[184:187], v[48:51]
	v_mfma_f32_16x16x32_bf16 v[48:51], v[172:175], v[188:191], v[48:51]
	v_mfma_f32_16x16x32_bf16 v[40:43], v[180:183], v[188:191], v[40:43]
	v_mfma_f32_16x16x32_bf16 v[40:43], v[176:179], v[184:187], v[40:43]
	v_mfma_f32_16x16x32_bf16 v[24:27], v[176:179], v[192:195], v[24:27]
	v_mfma_f32_16x16x32_bf16 v[24:27], v[180:183], v[196:199], v[24:27]
	v_mfma_f32_16x16x32_bf16 v[32:35], v[172:175], v[196:199], v[32:35]
	v_mfma_f32_16x16x32_bf16 v[32:35], v[168:171], v[192:195], v[32:35]
	v_mfma_f32_16x16x32_bf16 v[44:47], v[160:163], v[192:195], v[44:47]
	v_mfma_f32_16x16x32_bf16 v[44:47], v[164:167], v[196:199], v[44:47]
	v_mfma_f32_16x16x32_bf16 v[52:55], v[156:159], v[196:199], v[52:55]
	v_mfma_f32_16x16x32_bf16 v[52:55], v[144:147], v[192:195], v[52:55]
	v_mfma_f32_16x16x32_bf16 v[36:39], v[144:147], v[200:203], v[36:39]
	v_mfma_f32_16x16x32_bf16 v[36:39], v[156:159], v[204:207], v[36:39]
	v_mfma_f32_16x16x32_bf16 v[28:31], v[164:167], v[204:207], v[28:31]
	v_mfma_f32_16x16x32_bf16 v[28:31], v[160:163], v[200:203], v[28:31]
	v_mfma_f32_16x16x32_bf16 v[16:19], v[168:171], v[200:203], v[16:19]
	v_mfma_f32_16x16x32_bf16 v[16:19], v[172:175], v[204:207], v[16:19]
	v_mfma_f32_16x16x32_bf16 v[8:11], v[180:183], v[204:207], v[8:11]
	v_mfma_f32_16x16x32_bf16 v[8:11], v[176:179], v[200:203], v[8:11]
	v_mfma_f32_16x16x32_bf16 v[0:3], v[176:179], v[208:211], v[0:3]
	v_mfma_f32_16x16x32_bf16 v[0:3], v[180:183], v[212:215], v[0:3]
	v_mfma_f32_16x16x32_bf16 v[4:7], v[172:175], v[212:215], v[4:7]
	v_mfma_f32_16x16x32_bf16 v[4:7], v[168:171], v[208:211], v[4:7]
	v_mfma_f32_16x16x32_bf16 v[12:15], v[160:163], v[208:211], v[12:15]
	v_mfma_f32_16x16x32_bf16 v[12:15], v[164:167], v[212:215], v[12:15]
	v_mfma_f32_16x16x32_bf16 v[20:23], v[156:159], v[212:215], v[20:23]
	v_mfma_f32_16x16x32_bf16 v[20:23], v[144:147], v[208:211], v[20:23]
	s_setprio 0
	s_barrier
	s_add_i32 s57, 0, 0x18000
	v_add_u32_e32 v155, s57, v149
	s_add_i32 s58, 0, 0x1c000
	ds_read_b128 v[144:147], v155
	ds_read_b128 v[156:159], v155 offset:1024
	ds_read_b128 v[160:163], v155 offset:2048
	ds_read_b128 v[164:167], v155 offset:3072
	v_add_u32_e32 v155, s58, v149
	ds_read_b128 v[168:171], v155
	ds_read_b128 v[172:175], v155 offset:1024
	ds_read_b128 v[176:179], v155 offset:2048
	ds_read_b128 v[180:183], v155 offset:3072
	s_add_u32 s24, s34, 0x100000
	s_addc_u32 s25, s35, 0
	s_mov_b32 m0, s43
	v_lshl_add_u64 v[184:185], s[24:25], 0, v[128:129]
	global_load_lds_dwordx4 v[184:185], off
	v_lshl_add_u64 v[184:185], s[24:25], 0, v[132:133]
	s_mov_b32 m0, s44
	s_nop 0
	global_load_lds_dwordx4 v[184:185], off
	ds_read_b128 v[184:187], v154 offset:32768
	ds_read_b128 v[188:191], v154 offset:33792
	ds_read_b128 v[192:195], v154 offset:34816
	ds_read_b128 v[196:199], v154 offset:35840
	ds_read_b128 v[200:203], v154 offset:36864
	ds_read_b128 v[204:207], v154 offset:37888
	ds_read_b128 v[208:211], v154 offset:38912
	ds_read_b128 v[212:215], v154 offset:39936
	s_waitcnt vmcnt(8)
	s_waitcnt lgkmcnt(0)
	s_barrier
	s_waitcnt lgkmcnt(0)
	s_setprio 1
	v_mfma_f32_16x16x32_bf16 v[124:127], v[144:147], v[184:187], v[124:127]
	v_mfma_f32_16x16x32_bf16 v[124:127], v[156:159], v[188:191], v[124:127]
	v_mfma_f32_16x16x32_bf16 v[120:123], v[164:167], v[188:191], v[120:123]
	v_mfma_f32_16x16x32_bf16 v[120:123], v[160:163], v[184:187], v[120:123]
	v_mfma_f32_16x16x32_bf16 v[112:115], v[168:171], v[184:187], v[112:115]
	v_mfma_f32_16x16x32_bf16 v[112:115], v[172:175], v[188:191], v[112:115]
	v_mfma_f32_16x16x32_bf16 v[104:107], v[180:183], v[188:191], v[104:107]
	v_mfma_f32_16x16x32_bf16 v[104:107], v[176:179], v[184:187], v[104:107]
	v_mfma_f32_16x16x32_bf16 v[88:91], v[176:179], v[192:195], v[88:91]
	v_mfma_f32_16x16x32_bf16 v[88:91], v[180:183], v[196:199], v[88:91]
	v_mfma_f32_16x16x32_bf16 v[96:99], v[172:175], v[196:199], v[96:99]
	v_mfma_f32_16x16x32_bf16 v[96:99], v[168:171], v[192:195], v[96:99]
	v_mfma_f32_16x16x32_bf16 v[108:111], v[160:163], v[192:195], v[108:111]
	v_mfma_f32_16x16x32_bf16 v[108:111], v[164:167], v[196:199], v[108:111]
	v_mfma_f32_16x16x32_bf16 v[116:119], v[156:159], v[196:199], v[116:119]
	v_mfma_f32_16x16x32_bf16 v[116:119], v[144:147], v[192:195], v[116:119]
	v_mfma_f32_16x16x32_bf16 v[100:103], v[144:147], v[200:203], v[100:103]
	v_mfma_f32_16x16x32_bf16 v[100:103], v[156:159], v[204:207], v[100:103]
	v_mfma_f32_16x16x32_bf16 v[92:95], v[164:167], v[204:207], v[92:95]
	v_mfma_f32_16x16x32_bf16 v[92:95], v[160:163], v[200:203], v[92:95]
	v_mfma_f32_16x16x32_bf16 v[80:83], v[168:171], v[200:203], v[80:83]
	v_mfma_f32_16x16x32_bf16 v[80:83], v[172:175], v[204:207], v[80:83]
	v_mfma_f32_16x16x32_bf16 v[72:75], v[180:183], v[204:207], v[72:75]
	v_mfma_f32_16x16x32_bf16 v[72:75], v[176:179], v[200:203], v[72:75]
	v_mfma_f32_16x16x32_bf16 v[64:67], v[176:179], v[208:211], v[64:67]
	v_mfma_f32_16x16x32_bf16 v[64:67], v[180:183], v[212:215], v[64:67]
	v_mfma_f32_16x16x32_bf16 v[68:71], v[172:175], v[212:215], v[68:71]
	v_mfma_f32_16x16x32_bf16 v[68:71], v[168:171], v[208:211], v[68:71]
	v_mfma_f32_16x16x32_bf16 v[76:79], v[160:163], v[208:211], v[76:79]
	v_mfma_f32_16x16x32_bf16 v[76:79], v[164:167], v[212:215], v[76:79]
	v_mfma_f32_16x16x32_bf16 v[84:87], v[156:159], v[212:215], v[84:87]
	v_mfma_f32_16x16x32_bf16 v[84:87], v[144:147], v[208:211], v[84:87]
	s_setprio 0
	s_barrier
	s_add_i32 s24, s57, s41
	v_lshl_add_u64 v[184:185], v[216:217], 0, s[8:9]
	s_mov_b32 m0, s24
	s_nop 0
	global_load_lds_dwordx4 v[184:185], off
	s_add_i32 m0, s24, 0x2000
	s_add_u32 s24, s30, 0x100080
	v_lshl_add_u64 v[184:185], v[218:219], 0, s[8:9]
	s_addc_u32 s25, s31, 0
	s_add_i32 s30, s58, s41
	global_load_lds_dwordx4 v[184:185], off
	v_lshl_add_u64 v[184:185], s[24:25], 0, v[130:131]
	s_mov_b32 m0, s30
	s_nop 0
	global_load_lds_dwordx4 v[184:185], off
	v_lshl_add_u64 v[184:185], s[24:25], 0, v[134:135]
	s_add_i32 m0, s30, 0x2000
	s_nop 0
	global_load_lds_dwordx4 v[184:185], off
	v_lshl_add_u64 v[184:185], v[220:221], 0, s[8:9]
	s_mov_b32 m0, s46
	s_nop 0
	global_load_lds_dwordx4 v[184:185], off
	v_lshl_add_u64 v[184:185], v[222:223], 0, s[8:9]
	s_mov_b32 m0, s47
	s_nop 0
	global_load_lds_dwordx4 v[184:185], off
	ds_read_b128 v[184:187], v154 offset:49152
	ds_read_b128 v[188:191], v154 offset:50176
	ds_read_b128 v[192:195], v154 offset:51200
	ds_read_b128 v[196:199], v154 offset:52224
	ds_read_b128 v[200:203], v154 offset:53248
	ds_read_b128 v[204:207], v154 offset:54272
	ds_read_b128 v[208:211], v154 offset:55296
	ds_read_b128 v[212:215], v154 offset:56320
	s_waitcnt vmcnt(8)
	s_waitcnt lgkmcnt(0)
	s_barrier
	s_waitcnt lgkmcnt(0)
	s_setprio 1
	v_mfma_f32_16x16x32_bf16 v[60:63], v[144:147], v[184:187], v[60:63]
	v_mfma_f32_16x16x32_bf16 v[60:63], v[156:159], v[188:191], v[60:63]
	v_mfma_f32_16x16x32_bf16 v[56:59], v[164:167], v[188:191], v[56:59]
	v_mfma_f32_16x16x32_bf16 v[56:59], v[160:163], v[184:187], v[56:59]
	v_mfma_f32_16x16x32_bf16 v[48:51], v[168:171], v[184:187], v[48:51]
	v_mfma_f32_16x16x32_bf16 v[48:51], v[172:175], v[188:191], v[48:51]
	v_mfma_f32_16x16x32_bf16 v[40:43], v[180:183], v[188:191], v[40:43]
	v_mfma_f32_16x16x32_bf16 v[40:43], v[176:179], v[184:187], v[40:43]
	v_mfma_f32_16x16x32_bf16 v[24:27], v[176:179], v[192:195], v[24:27]
	v_mfma_f32_16x16x32_bf16 v[24:27], v[180:183], v[196:199], v[24:27]
	v_mfma_f32_16x16x32_bf16 v[32:35], v[172:175], v[196:199], v[32:35]
	v_mfma_f32_16x16x32_bf16 v[32:35], v[168:171], v[192:195], v[32:35]
	v_mfma_f32_16x16x32_bf16 v[44:47], v[160:163], v[192:195], v[44:47]
	v_mfma_f32_16x16x32_bf16 v[44:47], v[164:167], v[196:199], v[44:47]
	v_mfma_f32_16x16x32_bf16 v[52:55], v[156:159], v[196:199], v[52:55]
	v_mfma_f32_16x16x32_bf16 v[52:55], v[144:147], v[192:195], v[52:55]
	v_mfma_f32_16x16x32_bf16 v[36:39], v[144:147], v[200:203], v[36:39]
	v_mfma_f32_16x16x32_bf16 v[36:39], v[156:159], v[204:207], v[36:39]
	v_mfma_f32_16x16x32_bf16 v[28:31], v[164:167], v[204:207], v[28:31]
	v_mfma_f32_16x16x32_bf16 v[28:31], v[160:163], v[200:203], v[28:31]
	v_mfma_f32_16x16x32_bf16 v[16:19], v[168:171], v[200:203], v[16:19]
	v_mfma_f32_16x16x32_bf16 v[16:19], v[172:175], v[204:207], v[16:19]
	v_mfma_f32_16x16x32_bf16 v[8:11], v[180:183], v[204:207], v[8:11]
	v_mfma_f32_16x16x32_bf16 v[8:11], v[176:179], v[200:203], v[8:11]
	v_mfma_f32_16x16x32_bf16 v[0:3], v[176:179], v[208:211], v[0:3]
	v_mfma_f32_16x16x32_bf16 v[0:3], v[180:183], v[212:215], v[0:3]
	v_mfma_f32_16x16x32_bf16 v[4:7], v[172:175], v[212:215], v[4:7]
	v_mfma_f32_16x16x32_bf16 v[4:7], v[168:171], v[208:211], v[4:7]
	v_mfma_f32_16x16x32_bf16 v[12:15], v[160:163], v[208:211], v[12:15]
	v_mfma_f32_16x16x32_bf16 v[12:15], v[164:167], v[212:215], v[12:15]
	v_mfma_f32_16x16x32_bf16 v[20:23], v[156:159], v[212:215], v[20:23]
	v_mfma_f32_16x16x32_bf16 v[20:23], v[144:147], v[208:211], v[20:23]
	s_setprio 0
	s_barrier
	s_add_i32 s56, s56, 2
	s_add_u32 s54, s54, 0x100
	s_addc_u32 s55, s55, 0
	s_cmp_gt_u32 s56, 61
	s_mov_b64 s[24:25], s[28:29]
	s_cbranch_scc0 .LBB0_333
	s_and_b64 vcc, exec, s[0:1]
	s_cbranch_vccz .LBB0_336
	s_barrier

.LBB0_1202:
	ds_read_b128 v[128:131], v176
	ds_read_b128 v[132:135], v176 offset:1024
	ds_read_b128 v[136:139], v176 offset:2048
	ds_read_b128 v[140:143], v176 offset:3072
	ds_read_b128 v[144:147], v177
	ds_read_b128 v[148:151], v177 offset:1024
	ds_read_b128 v[180:183], v177 offset:2048
	ds_read_b128 v[184:187], v177 offset:3072
	s_add_u32 s30, s28, 0xfff00080
	s_addc_u32 s31, s29, -1
	s_cmp_eq_u32 s40, 60
	s_cselect_b32 s35, s23, s31
	s_cselect_b32 s34, s36, s30
	s_cselect_b32 s31, s21, s39
	s_cselect_b32 s30, s37, s38
	v_lshl_add_u64 v[172:173], s[28:29], 0, v[164:165]
	s_add_i32 m0, s7, 0xc000
	s_nop 0
	global_load_lds_dwordx4 v[172:173], off
	v_lshl_add_u64 v[172:173], s[28:29], 0, v[166:167]
	s_add_i32 m0, s7, 0xe000
	s_nop 0
	global_load_lds_dwordx4 v[172:173], off
	ds_read_b128 v[188:191], v178
	ds_read_b128 v[192:195], v178 offset:1024
	ds_read_b128 v[196:199], v178 offset:2048
	ds_read_b128 v[200:203], v178 offset:3072
	ds_read_b128 v[204:207], v178 offset:4096
	ds_read_b128 v[208:211], v178 offset:5120
	ds_read_b128 v[212:215], v178 offset:6144
	ds_read_b128 v[216:219], v178 offset:7168
	s_waitcnt vmcnt(8)
	s_waitcnt lgkmcnt(0)
	s_barrier
	s_waitcnt lgkmcnt(0)
	s_setprio 1
	v_mfma_f32_16x16x32_bf16 v[124:127], v[128:131], v[188:191], v[124:127]
	v_mfma_f32_16x16x32_bf16 v[124:127], v[132:135], v[192:195], v[124:127]
	v_mfma_f32_16x16x32_bf16 v[120:123], v[140:143], v[192:195], v[120:123]
	v_mfma_f32_16x16x32_bf16 v[120:123], v[136:139], v[188:191], v[120:123]
	v_mfma_f32_16x16x32_bf16 v[116:119], v[144:147], v[188:191], v[116:119]
	v_mfma_f32_16x16x32_bf16 v[116:119], v[148:151], v[192:195], v[116:119]
	v_mfma_f32_16x16x32_bf16 v[112:115], v[184:187], v[192:195], v[112:115]
	v_mfma_f32_16x16x32_bf16 v[112:115], v[180:183], v[188:191], v[112:115]
	v_mfma_f32_16x16x32_bf16 v[96:99], v[180:183], v[196:199], v[96:99]
	v_mfma_f32_16x16x32_bf16 v[96:99], v[184:187], v[200:203], v[96:99]
	v_mfma_f32_16x16x32_bf16 v[100:103], v[148:151], v[200:203], v[100:103]
	v_mfma_f32_16x16x32_bf16 v[100:103], v[144:147], v[196:199], v[100:103]
	v_mfma_f32_16x16x32_bf16 v[104:107], v[136:139], v[196:199], v[104:107]
	v_mfma_f32_16x16x32_bf16 v[104:107], v[140:143], v[200:203], v[104:107]
	v_mfma_f32_16x16x32_bf16 v[108:111], v[132:135], v[200:203], v[108:111]
	v_mfma_f32_16x16x32_bf16 v[108:111], v[128:131], v[196:199], v[108:111]
	v_mfma_f32_16x16x32_bf16 v[92:95], v[128:131], v[204:207], v[92:95]
	v_mfma_f32_16x16x32_bf16 v[92:95], v[132:135], v[208:211], v[92:95]
	v_mfma_f32_16x16x32_bf16 v[88:91], v[140:143], v[208:211], v[88:91]
	v_mfma_f32_16x16x32_bf16 v[88:91], v[136:139], v[204:207], v[88:91]
	v_mfma_f32_16x16x32_bf16 v[84:87], v[144:147], v[204:207], v[84:87]
	v_mfma_f32_16x16x32_bf16 v[84:87], v[148:151], v[208:211], v[84:87]
	v_mfma_f32_16x16x32_bf16 v[80:83], v[184:187], v[208:211], v[80:83]
	v_mfma_f32_16x16x32_bf16 v[80:83], v[180:183], v[204:207], v[80:83]
	v_mfma_f32_16x16x32_bf16 v[64:67], v[180:183], v[212:215], v[64:67]
	v_mfma_f32_16x16x32_bf16 v[64:67], v[184:187], v[216:219], v[64:67]
	v_mfma_f32_16x16x32_bf16 v[68:71], v[148:151], v[216:219], v[68:71]
	v_mfma_f32_16x16x32_bf16 v[68:71], v[144:147], v[212:215], v[68:71]
	v_mfma_f32_16x16x32_bf16 v[72:75], v[136:139], v[212:215], v[72:75]
	v_mfma_f32_16x16x32_bf16 v[72:75], v[140:143], v[216:219], v[72:75]
	v_mfma_f32_16x16x32_bf16 v[76:79], v[132:135], v[216:219], v[76:79]
	v_mfma_f32_16x16x32_bf16 v[76:79], v[128:131], v[212:215], v[76:79]
	s_setprio 0
	s_barrier
	s_add_i32 s41, s68, s33
	v_lshl_add_u64 v[172:173], s[30:31], 0, v[154:155]
	s_mov_b32 m0, s41
	v_lshl_add_u64 v[220:221], s[30:31], 0, v[158:159]
	global_load_lds_dwordx4 v[172:173], off
	s_add_i32 m0, s41, 0x2000
	s_add_u32 s42, s30, 0x100000
	s_addc_u32 s43, s31, 0
	s_add_i32 s41, s69, s33
	global_load_lds_dwordx4 v[220:221], off
	v_lshl_add_u64 v[188:189], s[42:43], 0, v[154:155]
	s_mov_b32 m0, s41
	v_lshl_add_u64 v[222:223], s[34:35], 0, v[152:153]
	global_load_lds_dwordx4 v[188:189], off
	v_lshl_add_u64 v[188:189], s[42:43], 0, v[158:159]
	s_add_i32 m0, s41, 0x2000
	v_lshl_add_u64 v[224:225], s[34:35], 0, v[156:157]
	global_load_lds_dwordx4 v[188:189], off
	s_mov_b32 m0, s7
	s_nop 0
	global_load_lds_dwordx4 v[222:223], off
	s_mov_b32 m0, s59
	s_nop 0
	global_load_lds_dwordx4 v[224:225], off
	ds_read_b128 v[188:191], v178 offset:16384
	ds_read_b128 v[192:195], v178 offset:17408
	ds_read_b128 v[196:199], v178 offset:18432
	ds_read_b128 v[200:203], v178 offset:19456
	ds_read_b128 v[204:207], v178 offset:20480
	ds_read_b128 v[208:211], v178 offset:21504
	ds_read_b128 v[212:215], v178 offset:22528
	ds_read_b128 v[216:219], v178 offset:23552
	s_waitcnt vmcnt(8)
	s_waitcnt lgkmcnt(0)
	s_barrier
	s_waitcnt lgkmcnt(0)
	s_setprio 1
	v_mfma_f32_16x16x32_bf16 v[60:63], v[128:131], v[188:191], v[60:63]
	v_mfma_f32_16x16x32_bf16 v[60:63], v[132:135], v[192:195], v[60:63]
	v_mfma_f32_16x16x32_bf16 v[56:59], v[140:143], v[192:195], v[56:59]
	v_mfma_f32_16x16x32_bf16 v[56:59], v[136:139], v[188:191], v[56:59]
	v_mfma_f32_16x16x32_bf16 v[52:55], v[144:147], v[188:191], v[52:55]
	v_mfma_f32_16x16x32_bf16 v[52:55], v[148:151], v[192:195], v[52:55]
	v_mfma_f32_16x16x32_bf16 v[48:51], v[184:187], v[192:195], v[48:51]
	v_mfma_f32_16x16x32_bf16 v[48:51], v[180:183], v[188:191], v[48:51]
	v_mfma_f32_16x16x32_bf16 v[32:35], v[180:183], v[196:199], v[32:35]
	v_mfma_f32_16x16x32_bf16 v[32:35], v[184:187], v[200:203], v[32:35]
	v_mfma_f32_16x16x32_bf16 v[36:39], v[148:151], v[200:203], v[36:39]
	v_mfma_f32_16x16x32_bf16 v[36:39], v[144:147], v[196:199], v[36:39]
	v_mfma_f32_16x16x32_bf16 v[40:43], v[136:139], v[196:199], v[40:43]
	v_mfma_f32_16x16x32_bf16 v[40:43], v[140:143], v[200:203], v[40:43]
	v_mfma_f32_16x16x32_bf16 v[44:47], v[132:135], v[200:203], v[44:47]
	v_mfma_f32_16x16x32_bf16 v[44:47], v[128:131], v[196:199], v[44:47]
	v_mfma_f32_16x16x32_bf16 v[28:31], v[128:131], v[204:207], v[28:31]
	v_mfma_f32_16x16x32_bf16 v[28:31], v[132:135], v[208:211], v[28:31]
	v_mfma_f32_16x16x32_bf16 v[24:27], v[140:143], v[208:211], v[24:27]
	v_mfma_f32_16x16x32_bf16 v[24:27], v[136:139], v[204:207], v[24:27]
	v_mfma_f32_16x16x32_bf16 v[20:23], v[144:147], v[204:207], v[20:23]
	v_mfma_f32_16x16x32_bf16 v[20:23], v[148:151], v[208:211], v[20:23]
	v_mfma_f32_16x16x32_bf16 v[16:19], v[184:187], v[208:211], v[16:19]
	v_mfma_f32_16x16x32_bf16 v[16:19], v[180:183], v[204:207], v[16:19]
	v_mfma_f32_16x16x32_bf16 v[0:3], v[180:183], v[212:215], v[0:3]
	v_mfma_f32_16x16x32_bf16 v[0:3], v[184:187], v[216:219], v[0:3]
	v_mfma_f32_16x16x32_bf16 v[4:7], v[148:151], v[216:219], v[4:7]
	v_mfma_f32_16x16x32_bf16 v[4:7], v[144:147], v[212:215], v[4:7]
	v_mfma_f32_16x16x32_bf16 v[8:11], v[136:139], v[212:215], v[8:11]
	v_mfma_f32_16x16x32_bf16 v[8:11], v[140:143], v[216:219], v[8:11]
	v_mfma_f32_16x16x32_bf16 v[12:15], v[132:135], v[216:219], v[12:15]
	v_mfma_f32_16x16x32_bf16 v[12:15], v[128:131], v[212:215], v[12:15]
	s_setprio 0
	s_barrier
	s_add_i32 s41, 0, 0x18000
	s_add_i32 s42, 0, 0x1c000
	v_add_u32_e32 v140, s41, v174
	v_add_u32_e32 v184, s42, v174
	ds_read_b128 v[128:131], v140
	ds_read_b128 v[132:135], v140 offset:1024
	ds_read_b128 v[136:139], v140 offset:2048
	ds_read_b128 v[140:143], v140 offset:3072
	ds_read_b128 v[144:147], v184
	ds_read_b128 v[148:151], v184 offset:1024
	ds_read_b128 v[180:183], v184 offset:2048
	ds_read_b128 v[184:187], v184 offset:3072
	s_add_u32 s34, s34, 0x100000
	s_addc_u32 s35, s35, 0
	s_mov_b32 m0, s60
	v_lshl_add_u64 v[188:189], s[34:35], 0, v[152:153]
	global_load_lds_dwordx4 v[188:189], off
	v_lshl_add_u64 v[188:189], s[34:35], 0, v[156:157]
	s_mov_b32 m0, s61
	s_nop 0
	global_load_lds_dwordx4 v[188:189], off
	ds_read_b128 v[188:191], v178 offset:32768
	ds_read_b128 v[192:195], v178 offset:33792
	ds_read_b128 v[196:199], v178 offset:34816
	ds_read_b128 v[200:203], v178 offset:35840
	ds_read_b128 v[204:207], v178 offset:36864
	ds_read_b128 v[208:211], v178 offset:37888
	ds_read_b128 v[212:215], v178 offset:38912
	ds_read_b128 v[216:219], v178 offset:39936
	s_waitcnt vmcnt(8)
	s_waitcnt lgkmcnt(0)
	s_barrier
	s_waitcnt lgkmcnt(0)
	s_setprio 1
	v_mfma_f32_16x16x32_bf16 v[124:127], v[128:131], v[188:191], v[124:127]
	v_mfma_f32_16x16x32_bf16 v[124:127], v[132:135], v[192:195], v[124:127]
	v_mfma_f32_16x16x32_bf16 v[120:123], v[140:143], v[192:195], v[120:123]
	v_mfma_f32_16x16x32_bf16 v[120:123], v[136:139], v[188:191], v[120:123]
	v_mfma_f32_16x16x32_bf16 v[116:119], v[144:147], v[188:191], v[116:119]
	v_mfma_f32_16x16x32_bf16 v[116:119], v[148:151], v[192:195], v[116:119]
	v_mfma_f32_16x16x32_bf16 v[112:115], v[184:187], v[192:195], v[112:115]
	v_mfma_f32_16x16x32_bf16 v[112:115], v[180:183], v[188:191], v[112:115]
	v_mfma_f32_16x16x32_bf16 v[96:99], v[180:183], v[196:199], v[96:99]
	v_mfma_f32_16x16x32_bf16 v[96:99], v[184:187], v[200:203], v[96:99]
	v_mfma_f32_16x16x32_bf16 v[100:103], v[148:151], v[200:203], v[100:103]
	v_mfma_f32_16x16x32_bf16 v[100:103], v[144:147], v[196:199], v[100:103]
	v_mfma_f32_16x16x32_bf16 v[104:107], v[136:139], v[196:199], v[104:107]
	v_mfma_f32_16x16x32_bf16 v[104:107], v[140:143], v[200:203], v[104:107]
	v_mfma_f32_16x16x32_bf16 v[108:111], v[132:135], v[200:203], v[108:111]
	v_mfma_f32_16x16x32_bf16 v[108:111], v[128:131], v[196:199], v[108:111]
	v_mfma_f32_16x16x32_bf16 v[92:95], v[128:131], v[204:207], v[92:95]
	v_mfma_f32_16x16x32_bf16 v[92:95], v[132:135], v[208:211], v[92:95]
	v_mfma_f32_16x16x32_bf16 v[88:91], v[140:143], v[208:211], v[88:91]
	v_mfma_f32_16x16x32_bf16 v[88:91], v[136:139], v[204:207], v[88:91]
	v_mfma_f32_16x16x32_bf16 v[84:87], v[144:147], v[204:207], v[84:87]
	v_mfma_f32_16x16x32_bf16 v[84:87], v[148:151], v[208:211], v[84:87]
	v_mfma_f32_16x16x32_bf16 v[80:83], v[184:187], v[208:211], v[80:83]
	v_mfma_f32_16x16x32_bf16 v[80:83], v[180:183], v[204:207], v[80:83]
	v_mfma_f32_16x16x32_bf16 v[64:67], v[180:183], v[212:215], v[64:67]
	v_mfma_f32_16x16x32_bf16 v[64:67], v[184:187], v[216:219], v[64:67]
	v_mfma_f32_16x16x32_bf16 v[68:71], v[148:151], v[216:219], v[68:71]
	v_mfma_f32_16x16x32_bf16 v[68:71], v[144:147], v[212:215], v[68:71]
	v_mfma_f32_16x16x32_bf16 v[72:75], v[136:139], v[212:215], v[72:75]
	v_mfma_f32_16x16x32_bf16 v[72:75], v[140:143], v[216:219], v[72:75]
	v_mfma_f32_16x16x32_bf16 v[76:79], v[132:135], v[216:219], v[76:79]
	v_mfma_f32_16x16x32_bf16 v[76:79], v[128:131], v[212:215], v[76:79]
	s_setprio 0
	s_barrier
	s_add_i32 s34, s41, s33
	v_lshl_add_u64 v[172:173], v[172:173], 0, s[16:17]
	s_mov_b32 m0, s34
	s_nop 0
	global_load_lds_dwordx4 v[172:173], off
	s_add_i32 m0, s34, 0x2000
	s_add_u32 s30, s30, 0x100800
	v_lshl_add_u64 v[172:173], v[220:221], 0, s[16:17]
	s_addc_u32 s31, s31, 0
	s_add_i32 s34, s42, s33
	global_load_lds_dwordx4 v[172:173], off
	v_lshl_add_u64 v[172:173], s[30:31], 0, v[154:155]
	s_mov_b32 m0, s34
	s_nop 0
	global_load_lds_dwordx4 v[172:173], off
	v_lshl_add_u64 v[172:173], s[30:31], 0, v[158:159]
	s_add_i32 m0, s34, 0x2000
	s_nop 0
	global_load_lds_dwordx4 v[172:173], off
	v_lshl_add_u64 v[172:173], v[222:223], 0, s[18:19]
	s_mov_b32 m0, s63
	s_nop 0
	global_load_lds_dwordx4 v[172:173], off
	v_lshl_add_u64 v[172:173], v[224:225], 0, s[18:19]
	s_mov_b32 m0, s64
	s_nop 0
	global_load_lds_dwordx4 v[172:173], off
	ds_read_b128 v[188:191], v178 offset:49152
	ds_read_b128 v[192:195], v178 offset:50176
	ds_read_b128 v[196:199], v178 offset:51200
	ds_read_b128 v[200:203], v178 offset:52224
	ds_read_b128 v[204:207], v178 offset:53248
	ds_read_b128 v[208:211], v178 offset:54272
	ds_read_b128 v[212:215], v178 offset:55296
	ds_read_b128 v[216:219], v178 offset:56320
	s_waitcnt vmcnt(8)
	s_waitcnt lgkmcnt(0)
	s_barrier
	s_waitcnt lgkmcnt(0)
	s_setprio 1
	v_mfma_f32_16x16x32_bf16 v[60:63], v[128:131], v[188:191], v[60:63]
	v_mfma_f32_16x16x32_bf16 v[60:63], v[132:135], v[192:195], v[60:63]
	v_mfma_f32_16x16x32_bf16 v[56:59], v[140:143], v[192:195], v[56:59]
	v_mfma_f32_16x16x32_bf16 v[56:59], v[136:139], v[188:191], v[56:59]
	v_mfma_f32_16x16x32_bf16 v[52:55], v[144:147], v[188:191], v[52:55]
	v_mfma_f32_16x16x32_bf16 v[52:55], v[148:151], v[192:195], v[52:55]
	v_mfma_f32_16x16x32_bf16 v[48:51], v[184:187], v[192:195], v[48:51]
	v_mfma_f32_16x16x32_bf16 v[48:51], v[180:183], v[188:191], v[48:51]
	v_mfma_f32_16x16x32_bf16 v[32:35], v[180:183], v[196:199], v[32:35]
	v_mfma_f32_16x16x32_bf16 v[32:35], v[184:187], v[200:203], v[32:35]
	v_mfma_f32_16x16x32_bf16 v[36:39], v[148:151], v[200:203], v[36:39]
	v_mfma_f32_16x16x32_bf16 v[36:39], v[144:147], v[196:199], v[36:39]
	v_mfma_f32_16x16x32_bf16 v[40:43], v[136:139], v[196:199], v[40:43]
	v_mfma_f32_16x16x32_bf16 v[40:43], v[140:143], v[200:203], v[40:43]
	v_mfma_f32_16x16x32_bf16 v[44:47], v[132:135], v[200:203], v[44:47]
	v_mfma_f32_16x16x32_bf16 v[44:47], v[128:131], v[196:199], v[44:47]
	v_mfma_f32_16x16x32_bf16 v[28:31], v[128:131], v[204:207], v[28:31]
	v_mfma_f32_16x16x32_bf16 v[28:31], v[132:135], v[208:211], v[28:31]
	v_mfma_f32_16x16x32_bf16 v[24:27], v[140:143], v[208:211], v[24:27]
	v_mfma_f32_16x16x32_bf16 v[24:27], v[136:139], v[204:207], v[24:27]
	v_mfma_f32_16x16x32_bf16 v[20:23], v[144:147], v[204:207], v[20:23]
	v_mfma_f32_16x16x32_bf16 v[20:23], v[148:151], v[208:211], v[20:23]
	v_mfma_f32_16x16x32_bf16 v[16:19], v[184:187], v[208:211], v[16:19]
	v_mfma_f32_16x16x32_bf16 v[16:19], v[180:183], v[204:207], v[16:19]
	v_mfma_f32_16x16x32_bf16 v[0:3], v[180:183], v[212:215], v[0:3]
	v_mfma_f32_16x16x32_bf16 v[0:3], v[184:187], v[216:219], v[0:3]
	v_mfma_f32_16x16x32_bf16 v[4:7], v[148:151], v[216:219], v[4:7]
	v_mfma_f32_16x16x32_bf16 v[4:7], v[144:147], v[212:215], v[4:7]
	v_mfma_f32_16x16x32_bf16 v[8:11], v[136:139], v[212:215], v[8:11]
	v_mfma_f32_16x16x32_bf16 v[8:11], v[140:143], v[216:219], v[8:11]
	v_mfma_f32_16x16x32_bf16 v[12:15], v[132:135], v[216:219], v[12:15]
	v_mfma_f32_16x16x32_bf16 v[12:15], v[128:131], v[212:215], v[12:15]
	s_setprio 0
	s_barrier
	s_add_i32 s40, s40, 2
	s_add_u32 s38, s38, 0x1000
	s_addc_u32 s39, s39, 0
	s_add_u32 s28, s28, 0x100
	s_addc_u32 s29, s29, 0
	s_cmp_gt_u32 s40, 61
	s_cbranch_scc0 .LBB0_1202
	s_and_b64 vcc, exec, s[10:11]
	s_cbranch_vccz .LBB0_1205
	s_barrier

.LBB0_1263:
	ds_read_b128 v[146:149], v152
	ds_read_b128 v[156:159], v152 offset:1024
	ds_read_b128 v[160:163], v152 offset:2048
	ds_read_b128 v[164:167], v152 offset:3072
	ds_read_b128 v[168:171], v153
	ds_read_b128 v[172:175], v153 offset:1024
	ds_read_b128 v[176:179], v153 offset:2048
	ds_read_b128 v[180:183], v153 offset:3072
	s_add_u32 s22, s20, 0x100
	s_addc_u32 s23, s21, 0
	s_cmp_eq_u32 s46, 12
	s_cselect_b32 s27, s5, s23
	s_cselect_b32 s26, s4, s22
	s_cselect_b32 s25, s19, s15
	s_cselect_b32 s24, s18, s6
	v_lshl_add_u64 v[184:185], s[20:21], 0, v[136:137]
	s_add_i32 m0, s17, 0xc000
	s_nop 0
	global_load_lds_dwordx4 v[184:185], off
	v_lshl_add_u64 v[184:185], s[20:21], 0, v[138:139]
	s_add_i32 m0, s17, 0xe000
	s_nop 0
	global_load_lds_dwordx4 v[184:185], off
	ds_read_b128 v[184:187], v154
	ds_read_b128 v[188:191], v154 offset:1024
	ds_read_b128 v[192:195], v154 offset:2048
	ds_read_b128 v[196:199], v154 offset:3072
	ds_read_b128 v[200:203], v154 offset:4096
	ds_read_b128 v[204:207], v154 offset:5120
	ds_read_b128 v[208:211], v154 offset:6144
	ds_read_b128 v[212:215], v154 offset:7168
	s_waitcnt vmcnt(8)
	s_waitcnt lgkmcnt(0)
	s_barrier
	s_waitcnt lgkmcnt(0)
	s_setprio 1
	v_mfma_f32_16x16x32_bf16 v[124:127], v[146:149], v[184:187], v[124:127]
	v_mfma_f32_16x16x32_bf16 v[124:127], v[156:159], v[188:191], v[124:127]
	v_mfma_f32_16x16x32_bf16 v[120:123], v[164:167], v[188:191], v[120:123]
	v_mfma_f32_16x16x32_bf16 v[120:123], v[160:163], v[184:187], v[120:123]
	v_mfma_f32_16x16x32_bf16 v[116:119], v[168:171], v[184:187], v[116:119]
	v_mfma_f32_16x16x32_bf16 v[116:119], v[172:175], v[188:191], v[116:119]
	v_mfma_f32_16x16x32_bf16 v[108:111], v[180:183], v[188:191], v[108:111]
	v_mfma_f32_16x16x32_bf16 v[108:111], v[176:179], v[184:187], v[108:111]
	v_mfma_f32_16x16x32_bf16 v[92:95], v[176:179], v[192:195], v[92:95]
	v_mfma_f32_16x16x32_bf16 v[92:95], v[180:183], v[196:199], v[92:95]
	v_mfma_f32_16x16x32_bf16 v[100:103], v[172:175], v[196:199], v[100:103]
	v_mfma_f32_16x16x32_bf16 v[100:103], v[168:171], v[192:195], v[100:103]
	v_mfma_f32_16x16x32_bf16 v[104:107], v[160:163], v[192:195], v[104:107]
	v_mfma_f32_16x16x32_bf16 v[104:107], v[164:167], v[196:199], v[104:107]
	v_mfma_f32_16x16x32_bf16 v[112:115], v[156:159], v[196:199], v[112:115]
	v_mfma_f32_16x16x32_bf16 v[112:115], v[146:149], v[192:195], v[112:115]
	v_mfma_f32_16x16x32_bf16 v[96:99], v[146:149], v[200:203], v[96:99]
	v_mfma_f32_16x16x32_bf16 v[96:99], v[156:159], v[204:207], v[96:99]
	v_mfma_f32_16x16x32_bf16 v[88:91], v[164:167], v[204:207], v[88:91]
	v_mfma_f32_16x16x32_bf16 v[88:91], v[160:163], v[200:203], v[88:91]
	v_mfma_f32_16x16x32_bf16 v[84:87], v[168:171], v[200:203], v[84:87]
	v_mfma_f32_16x16x32_bf16 v[84:87], v[172:175], v[204:207], v[84:87]
	v_mfma_f32_16x16x32_bf16 v[76:79], v[180:183], v[204:207], v[76:79]
	v_mfma_f32_16x16x32_bf16 v[76:79], v[176:179], v[200:203], v[76:79]
	v_mfma_f32_16x16x32_bf16 v[64:67], v[176:179], v[208:211], v[64:67]
	v_mfma_f32_16x16x32_bf16 v[64:67], v[180:183], v[212:215], v[64:67]
	v_mfma_f32_16x16x32_bf16 v[68:71], v[172:175], v[212:215], v[68:71]
	v_mfma_f32_16x16x32_bf16 v[68:71], v[168:171], v[208:211], v[68:71]
	v_mfma_f32_16x16x32_bf16 v[72:75], v[160:163], v[208:211], v[72:75]
	v_mfma_f32_16x16x32_bf16 v[72:75], v[164:167], v[212:215], v[72:75]
	v_mfma_f32_16x16x32_bf16 v[80:83], v[156:159], v[212:215], v[80:83]
	v_mfma_f32_16x16x32_bf16 v[80:83], v[146:149], v[208:211], v[80:83]
	s_setprio 0
	s_barrier
	s_add_i32 s20, s41, s33
	v_lshl_add_u64 v[216:217], s[24:25], 0, v[130:131]
	s_mov_b32 m0, s20
	v_lshl_add_u64 v[218:219], s[24:25], 0, v[134:135]
	global_load_lds_dwordx4 v[216:217], off
	s_add_i32 m0, s20, 0x2000
	s_add_u32 s20, s24, 0x200000
	s_addc_u32 s21, s25, 0
	s_add_i32 s47, s42, s33
	global_load_lds_dwordx4 v[218:219], off
	v_lshl_add_u64 v[184:185], s[20:21], 0, v[130:131]
	s_mov_b32 m0, s47
	v_lshl_add_u64 v[220:221], s[26:27], 0, v[128:129]
	global_load_lds_dwordx4 v[184:185], off
	v_lshl_add_u64 v[184:185], s[20:21], 0, v[134:135]
	s_add_i32 m0, s47, 0x2000
	v_lshl_add_u64 v[222:223], s[26:27], 0, v[132:133]
	global_load_lds_dwordx4 v[184:185], off
	s_mov_b32 m0, s17
	s_nop 0
	global_load_lds_dwordx4 v[220:221], off
	s_mov_b32 m0, s34
	s_nop 0
	global_load_lds_dwordx4 v[222:223], off
	ds_read_b128 v[184:187], v154 offset:16384
	ds_read_b128 v[188:191], v154 offset:17408
	ds_read_b128 v[192:195], v154 offset:18432
	ds_read_b128 v[196:199], v154 offset:19456
	ds_read_b128 v[200:203], v154 offset:20480
	ds_read_b128 v[204:207], v154 offset:21504
	ds_read_b128 v[208:211], v154 offset:22528
	ds_read_b128 v[212:215], v154 offset:23552
	s_waitcnt vmcnt(8)
	s_waitcnt lgkmcnt(0)
	s_barrier
	s_waitcnt lgkmcnt(0)
	s_setprio 1
	v_mfma_f32_16x16x32_bf16 v[60:63], v[146:149], v[184:187], v[60:63]
	v_mfma_f32_16x16x32_bf16 v[60:63], v[156:159], v[188:191], v[60:63]
	v_mfma_f32_16x16x32_bf16 v[56:59], v[164:167], v[188:191], v[56:59]
	v_mfma_f32_16x16x32_bf16 v[56:59], v[160:163], v[184:187], v[56:59]
	v_mfma_f32_16x16x32_bf16 v[52:55], v[168:171], v[184:187], v[52:55]
	v_mfma_f32_16x16x32_bf16 v[52:55], v[172:175], v[188:191], v[52:55]
	v_mfma_f32_16x16x32_bf16 v[44:47], v[180:183], v[188:191], v[44:47]
	v_mfma_f32_16x16x32_bf16 v[44:47], v[176:179], v[184:187], v[44:47]
	v_mfma_f32_16x16x32_bf16 v[28:31], v[176:179], v[192:195], v[28:31]
	v_mfma_f32_16x16x32_bf16 v[28:31], v[180:183], v[196:199], v[28:31]
	v_mfma_f32_16x16x32_bf16 v[36:39], v[172:175], v[196:199], v[36:39]
	v_mfma_f32_16x16x32_bf16 v[36:39], v[168:171], v[192:195], v[36:39]
	v_mfma_f32_16x16x32_bf16 v[40:43], v[160:163], v[192:195], v[40:43]
	v_mfma_f32_16x16x32_bf16 v[40:43], v[164:167], v[196:199], v[40:43]
	v_mfma_f32_16x16x32_bf16 v[48:51], v[156:159], v[196:199], v[48:51]
	v_mfma_f32_16x16x32_bf16 v[48:51], v[146:149], v[192:195], v[48:51]
	v_mfma_f32_16x16x32_bf16 v[32:35], v[146:149], v[200:203], v[32:35]
	v_mfma_f32_16x16x32_bf16 v[32:35], v[156:159], v[204:207], v[32:35]
	v_mfma_f32_16x16x32_bf16 v[24:27], v[164:167], v[204:207], v[24:27]
	v_mfma_f32_16x16x32_bf16 v[24:27], v[160:163], v[200:203], v[24:27]
	v_mfma_f32_16x16x32_bf16 v[20:23], v[168:171], v[200:203], v[20:23]
	v_mfma_f32_16x16x32_bf16 v[20:23], v[172:175], v[204:207], v[20:23]
	v_mfma_f32_16x16x32_bf16 v[12:15], v[180:183], v[204:207], v[12:15]
	v_mfma_f32_16x16x32_bf16 v[12:15], v[176:179], v[200:203], v[12:15]
	v_mfma_f32_16x16x32_bf16 v[0:3], v[176:179], v[208:211], v[0:3]
	v_mfma_f32_16x16x32_bf16 v[0:3], v[180:183], v[212:215], v[0:3]
	v_mfma_f32_16x16x32_bf16 v[4:7], v[172:175], v[212:215], v[4:7]
	v_mfma_f32_16x16x32_bf16 v[4:7], v[168:171], v[208:211], v[4:7]
	v_mfma_f32_16x16x32_bf16 v[8:11], v[160:163], v[208:211], v[8:11]
	v_mfma_f32_16x16x32_bf16 v[8:11], v[164:167], v[212:215], v[8:11]
	v_mfma_f32_16x16x32_bf16 v[16:19], v[156:159], v[212:215], v[16:19]
	v_mfma_f32_16x16x32_bf16 v[16:19], v[146:149], v[208:211], v[16:19]
	s_setprio 0
	s_barrier
	s_add_i32 s47, 0, 0x18000
	v_add_u32_e32 v144, s47, v145
	s_add_i32 s48, 0, 0x1c000
	ds_read_b128 v[146:149], v144
	ds_read_b128 v[156:159], v144 offset:1024
	ds_read_b128 v[160:163], v144 offset:2048
	ds_read_b128 v[164:167], v144 offset:3072
	v_add_u32_e32 v144, s48, v145
	ds_read_b128 v[168:171], v144
	ds_read_b128 v[172:175], v144 offset:1024
	ds_read_b128 v[176:179], v144 offset:2048
	ds_read_b128 v[180:183], v144 offset:3072
	s_add_u32 s20, s26, 0x200000
	s_addc_u32 s21, s27, 0
	s_mov_b32 m0, s35
	v_lshl_add_u64 v[184:185], s[20:21], 0, v[128:129]
	global_load_lds_dwordx4 v[184:185], off
	v_lshl_add_u64 v[184:185], s[20:21], 0, v[132:133]
	s_mov_b32 m0, s36
	s_nop 0
	global_load_lds_dwordx4 v[184:185], off
	ds_read_b128 v[184:187], v154 offset:32768
	ds_read_b128 v[188:191], v154 offset:33792
	ds_read_b128 v[192:195], v154 offset:34816
	ds_read_b128 v[196:199], v154 offset:35840
	ds_read_b128 v[200:203], v154 offset:36864
	ds_read_b128 v[204:207], v154 offset:37888
	ds_read_b128 v[208:211], v154 offset:38912
	ds_read_b128 v[212:215], v154 offset:39936
	s_waitcnt vmcnt(8)
	s_waitcnt lgkmcnt(0)
	s_barrier
	s_waitcnt lgkmcnt(0)
	s_setprio 1
	v_mfma_f32_16x16x32_bf16 v[124:127], v[146:149], v[184:187], v[124:127]
	v_mfma_f32_16x16x32_bf16 v[124:127], v[156:159], v[188:191], v[124:127]
	v_mfma_f32_16x16x32_bf16 v[120:123], v[164:167], v[188:191], v[120:123]
	v_mfma_f32_16x16x32_bf16 v[120:123], v[160:163], v[184:187], v[120:123]
	v_mfma_f32_16x16x32_bf16 v[116:119], v[168:171], v[184:187], v[116:119]
	v_mfma_f32_16x16x32_bf16 v[116:119], v[172:175], v[188:191], v[116:119]
	v_mfma_f32_16x16x32_bf16 v[108:111], v[180:183], v[188:191], v[108:111]
	v_mfma_f32_16x16x32_bf16 v[108:111], v[176:179], v[184:187], v[108:111]
	v_mfma_f32_16x16x32_bf16 v[92:95], v[176:179], v[192:195], v[92:95]
	v_mfma_f32_16x16x32_bf16 v[92:95], v[180:183], v[196:199], v[92:95]
	v_mfma_f32_16x16x32_bf16 v[100:103], v[172:175], v[196:199], v[100:103]
	v_mfma_f32_16x16x32_bf16 v[100:103], v[168:171], v[192:195], v[100:103]
	v_mfma_f32_16x16x32_bf16 v[104:107], v[160:163], v[192:195], v[104:107]
	v_mfma_f32_16x16x32_bf16 v[104:107], v[164:167], v[196:199], v[104:107]
	v_mfma_f32_16x16x32_bf16 v[112:115], v[156:159], v[196:199], v[112:115]
	v_mfma_f32_16x16x32_bf16 v[112:115], v[146:149], v[192:195], v[112:115]
	v_mfma_f32_16x16x32_bf16 v[96:99], v[146:149], v[200:203], v[96:99]
	v_mfma_f32_16x16x32_bf16 v[96:99], v[156:159], v[204:207], v[96:99]
	v_mfma_f32_16x16x32_bf16 v[88:91], v[164:167], v[204:207], v[88:91]
	v_mfma_f32_16x16x32_bf16 v[88:91], v[160:163], v[200:203], v[88:91]
	v_mfma_f32_16x16x32_bf16 v[84:87], v[168:171], v[200:203], v[84:87]
	v_mfma_f32_16x16x32_bf16 v[84:87], v[172:175], v[204:207], v[84:87]
	v_mfma_f32_16x16x32_bf16 v[76:79], v[180:183], v[204:207], v[76:79]
	v_mfma_f32_16x16x32_bf16 v[76:79], v[176:179], v[200:203], v[76:79]
	v_mfma_f32_16x16x32_bf16 v[64:67], v[176:179], v[208:211], v[64:67]
	v_mfma_f32_16x16x32_bf16 v[64:67], v[180:183], v[212:215], v[64:67]
	v_mfma_f32_16x16x32_bf16 v[68:71], v[172:175], v[212:215], v[68:71]
	v_mfma_f32_16x16x32_bf16 v[68:71], v[168:171], v[208:211], v[68:71]
	v_mfma_f32_16x16x32_bf16 v[72:75], v[160:163], v[208:211], v[72:75]
	v_mfma_f32_16x16x32_bf16 v[72:75], v[164:167], v[212:215], v[72:75]
	v_mfma_f32_16x16x32_bf16 v[80:83], v[156:159], v[212:215], v[80:83]
	v_mfma_f32_16x16x32_bf16 v[80:83], v[146:149], v[208:211], v[80:83]
	s_setprio 0
	s_barrier
	s_add_i32 s20, s47, s33
	v_lshl_add_u64 v[184:185], v[216:217], 0, s[12:13]
	s_mov_b32 m0, s20
	s_nop 0
	global_load_lds_dwordx4 v[184:185], off
	s_add_i32 m0, s20, 0x2000
	s_add_u32 s20, s24, 0x200080
	v_lshl_add_u64 v[184:185], v[218:219], 0, s[12:13]
	s_addc_u32 s21, s25, 0
	s_add_i32 s24, s48, s33
	global_load_lds_dwordx4 v[184:185], off
	v_lshl_add_u64 v[184:185], s[20:21], 0, v[130:131]
	s_mov_b32 m0, s24
	s_nop 0
	global_load_lds_dwordx4 v[184:185], off
	v_lshl_add_u64 v[184:185], s[20:21], 0, v[134:135]
	s_add_i32 m0, s24, 0x2000
	s_nop 0
	global_load_lds_dwordx4 v[184:185], off
	v_lshl_add_u64 v[184:185], v[220:221], 0, s[12:13]
	s_mov_b32 m0, s37
	s_nop 0
	global_load_lds_dwordx4 v[184:185], off
	v_lshl_add_u64 v[184:185], v[222:223], 0, s[12:13]
	s_mov_b32 m0, s38
	s_nop 0
	global_load_lds_dwordx4 v[184:185], off
	ds_read_b128 v[184:187], v154 offset:49152
	ds_read_b128 v[188:191], v154 offset:50176
	ds_read_b128 v[192:195], v154 offset:51200
	ds_read_b128 v[196:199], v154 offset:52224
	ds_read_b128 v[200:203], v154 offset:53248
	ds_read_b128 v[204:207], v154 offset:54272
	ds_read_b128 v[208:211], v154 offset:55296
	ds_read_b128 v[212:215], v154 offset:56320
	s_waitcnt vmcnt(8)
	s_waitcnt lgkmcnt(0)
	s_barrier
	s_waitcnt lgkmcnt(0)
	s_setprio 1
	v_mfma_f32_16x16x32_bf16 v[60:63], v[146:149], v[184:187], v[60:63]
	v_mfma_f32_16x16x32_bf16 v[60:63], v[156:159], v[188:191], v[60:63]
	v_mfma_f32_16x16x32_bf16 v[56:59], v[164:167], v[188:191], v[56:59]
	v_mfma_f32_16x16x32_bf16 v[56:59], v[160:163], v[184:187], v[56:59]
	v_mfma_f32_16x16x32_bf16 v[52:55], v[168:171], v[184:187], v[52:55]
	v_mfma_f32_16x16x32_bf16 v[52:55], v[172:175], v[188:191], v[52:55]
	v_mfma_f32_16x16x32_bf16 v[44:47], v[180:183], v[188:191], v[44:47]
	v_mfma_f32_16x16x32_bf16 v[44:47], v[176:179], v[184:187], v[44:47]
	v_mfma_f32_16x16x32_bf16 v[28:31], v[176:179], v[192:195], v[28:31]
	v_mfma_f32_16x16x32_bf16 v[28:31], v[180:183], v[196:199], v[28:31]
	v_mfma_f32_16x16x32_bf16 v[36:39], v[172:175], v[196:199], v[36:39]
	v_mfma_f32_16x16x32_bf16 v[36:39], v[168:171], v[192:195], v[36:39]
	v_mfma_f32_16x16x32_bf16 v[40:43], v[160:163], v[192:195], v[40:43]
	v_mfma_f32_16x16x32_bf16 v[40:43], v[164:167], v[196:199], v[40:43]
	v_mfma_f32_16x16x32_bf16 v[48:51], v[156:159], v[196:199], v[48:51]
	v_mfma_f32_16x16x32_bf16 v[48:51], v[146:149], v[192:195], v[48:51]
	v_mfma_f32_16x16x32_bf16 v[32:35], v[146:149], v[200:203], v[32:35]
	v_mfma_f32_16x16x32_bf16 v[32:35], v[156:159], v[204:207], v[32:35]
	v_mfma_f32_16x16x32_bf16 v[24:27], v[164:167], v[204:207], v[24:27]
	v_mfma_f32_16x16x32_bf16 v[24:27], v[160:163], v[200:203], v[24:27]
	v_mfma_f32_16x16x32_bf16 v[20:23], v[168:171], v[200:203], v[20:23]
	v_mfma_f32_16x16x32_bf16 v[20:23], v[172:175], v[204:207], v[20:23]
	v_mfma_f32_16x16x32_bf16 v[12:15], v[180:183], v[204:207], v[12:15]
	v_mfma_f32_16x16x32_bf16 v[12:15], v[176:179], v[200:203], v[12:15]
	v_mfma_f32_16x16x32_bf16 v[0:3], v[176:179], v[208:211], v[0:3]
	v_mfma_f32_16x16x32_bf16 v[0:3], v[180:183], v[212:215], v[0:3]
	v_mfma_f32_16x16x32_bf16 v[4:7], v[172:175], v[212:215], v[4:7]
	v_mfma_f32_16x16x32_bf16 v[4:7], v[168:171], v[208:211], v[4:7]
	v_mfma_f32_16x16x32_bf16 v[8:11], v[160:163], v[208:211], v[8:11]
	v_mfma_f32_16x16x32_bf16 v[8:11], v[164:167], v[212:215], v[8:11]
	v_mfma_f32_16x16x32_bf16 v[16:19], v[156:159], v[212:215], v[16:19]
	v_mfma_f32_16x16x32_bf16 v[16:19], v[146:149], v[208:211], v[16:19]
	s_setprio 0
	s_barrier
	s_add_i32 s46, s46, 2
	s_add_u32 s6, s6, 0x100
	s_addc_u32 s15, s15, 0
	s_cmp_gt_u32 s46, 13
	s_mov_b64 s[20:21], s[22:23]
	s_cbranch_scc0 .LBB0_1263
	s_and_b64 vcc, exec, s[8:9]
	s_cbranch_vccz .LBB0_1266
	s_barrier

.LBB0_1340:
	v_add_u32_e32 v166, s51, v152
	v_add_u32_e32 v182, s52, v152
	ds_read_b128 v[154:157], v166
	ds_read_b128 v[158:161], v166 offset:1024
	ds_read_b128 v[162:165], v166 offset:2048
	ds_read_b128 v[166:169], v166 offset:3072
	ds_read_b128 v[170:173], v182
	ds_read_b128 v[174:177], v182 offset:1024
	ds_read_b128 v[178:181], v182 offset:2048
	ds_read_b128 v[182:185], v182 offset:3072
	s_add_u32 s30, s10, s28
	s_addc_u32 s31, s11, s29
	s_cmp_eq_u32 s58, 60
	s_cselect_b32 s35, s23, s31
	s_cselect_b32 s34, s54, s30
	s_cselect_b32 s31, s21, s57
	s_cselect_b32 s30, s55, s56
	v_lshl_add_u64 v[186:187], s[10:11], 0, v[146:147]
	s_add_i32 m0, s44, 0xc000
	s_nop 0
	global_load_lds_dwordx4 v[186:187], off
	v_lshl_add_u64 v[186:187], s[10:11], 0, v[144:145]
	s_add_i32 m0, s44, 0xe000
	s_nop 0
	global_load_lds_dwordx4 v[186:187], off
	ds_read_b128 v[186:189], v153
	ds_read_b128 v[190:193], v153 offset:1024
	ds_read_b128 v[194:197], v153 offset:2048
	ds_read_b128 v[198:201], v153 offset:3072
	ds_read_b128 v[202:205], v153 offset:4096
	ds_read_b128 v[206:209], v153 offset:5120
	ds_read_b128 v[210:213], v153 offset:6144
	ds_read_b128 v[214:217], v153 offset:7168
	s_waitcnt vmcnt(8)
	s_waitcnt lgkmcnt(0)
	s_barrier
	s_waitcnt lgkmcnt(0)
	s_setprio 1
	v_mfma_f32_16x16x32_bf16 v[124:127], v[154:157], v[186:189], v[124:127]
	v_mfma_f32_16x16x32_bf16 v[124:127], v[158:161], v[190:193], v[124:127]
	v_mfma_f32_16x16x32_bf16 v[120:123], v[166:169], v[190:193], v[120:123]
	v_mfma_f32_16x16x32_bf16 v[120:123], v[162:165], v[186:189], v[120:123]
	v_mfma_f32_16x16x32_bf16 v[116:119], v[170:173], v[186:189], v[116:119]
	v_mfma_f32_16x16x32_bf16 v[116:119], v[174:177], v[190:193], v[116:119]
	v_mfma_f32_16x16x32_bf16 v[112:115], v[182:185], v[190:193], v[112:115]
	v_mfma_f32_16x16x32_bf16 v[112:115], v[178:181], v[186:189], v[112:115]
	v_mfma_f32_16x16x32_bf16 v[96:99], v[178:181], v[194:197], v[96:99]
	v_mfma_f32_16x16x32_bf16 v[96:99], v[182:185], v[198:201], v[96:99]
	v_mfma_f32_16x16x32_bf16 v[100:103], v[174:177], v[198:201], v[100:103]
	v_mfma_f32_16x16x32_bf16 v[100:103], v[170:173], v[194:197], v[100:103]
	v_mfma_f32_16x16x32_bf16 v[104:107], v[162:165], v[194:197], v[104:107]
	v_mfma_f32_16x16x32_bf16 v[104:107], v[166:169], v[198:201], v[104:107]
	v_mfma_f32_16x16x32_bf16 v[108:111], v[158:161], v[198:201], v[108:111]
	v_mfma_f32_16x16x32_bf16 v[108:111], v[154:157], v[194:197], v[108:111]
	v_mfma_f32_16x16x32_bf16 v[92:95], v[154:157], v[202:205], v[92:95]
	v_mfma_f32_16x16x32_bf16 v[92:95], v[158:161], v[206:209], v[92:95]
	v_mfma_f32_16x16x32_bf16 v[88:91], v[166:169], v[206:209], v[88:91]
	v_mfma_f32_16x16x32_bf16 v[88:91], v[162:165], v[202:205], v[88:91]
	v_mfma_f32_16x16x32_bf16 v[84:87], v[170:173], v[202:205], v[84:87]
	v_mfma_f32_16x16x32_bf16 v[84:87], v[174:177], v[206:209], v[84:87]
	v_mfma_f32_16x16x32_bf16 v[80:83], v[182:185], v[206:209], v[80:83]
	v_mfma_f32_16x16x32_bf16 v[80:83], v[178:181], v[202:205], v[80:83]
	v_mfma_f32_16x16x32_bf16 v[64:67], v[178:181], v[210:213], v[64:67]
	v_mfma_f32_16x16x32_bf16 v[64:67], v[182:185], v[214:217], v[64:67]
	v_mfma_f32_16x16x32_bf16 v[68:71], v[174:177], v[214:217], v[68:71]
	v_mfma_f32_16x16x32_bf16 v[68:71], v[170:173], v[210:213], v[68:71]
	v_mfma_f32_16x16x32_bf16 v[72:75], v[162:165], v[210:213], v[72:75]
	v_mfma_f32_16x16x32_bf16 v[72:75], v[166:169], v[214:217], v[72:75]
	v_mfma_f32_16x16x32_bf16 v[76:79], v[158:161], v[214:217], v[76:79]
	v_mfma_f32_16x16x32_bf16 v[76:79], v[154:157], v[210:213], v[76:79]
	s_setprio 0
	s_barrier
	s_add_i32 s59, s51, s43
	v_lshl_add_u64 v[218:219], s[30:31], 0, v[130:131]
	s_mov_b32 m0, s59
	v_lshl_add_u64 v[220:221], s[30:31], 0, v[134:135]
	global_load_lds_dwordx4 v[218:219], off
	s_add_i32 m0, s59, 0x2000
	s_add_u32 s60, s30, 0x100000
	s_addc_u32 s61, s31, 0
	s_add_i32 s59, s52, s43
	global_load_lds_dwordx4 v[220:221], off
	v_lshl_add_u64 v[186:187], s[60:61], 0, v[130:131]
	s_mov_b32 m0, s59
	v_lshl_add_u64 v[222:223], s[34:35], 0, v[128:129]
	global_load_lds_dwordx4 v[186:187], off
	v_lshl_add_u64 v[186:187], s[60:61], 0, v[134:135]
	s_add_i32 m0, s59, 0x2000
	v_lshl_add_u64 v[224:225], s[34:35], 0, v[132:133]
	global_load_lds_dwordx4 v[186:187], off
	s_mov_b32 m0, s44
	s_nop 0
	global_load_lds_dwordx4 v[222:223], off
	s_mov_b32 m0, s45
	s_nop 0
	global_load_lds_dwordx4 v[224:225], off
	ds_read_b128 v[186:189], v153 offset:16384
	ds_read_b128 v[190:193], v153 offset:17408
	ds_read_b128 v[194:197], v153 offset:18432
	ds_read_b128 v[198:201], v153 offset:19456
	ds_read_b128 v[202:205], v153 offset:20480
	ds_read_b128 v[206:209], v153 offset:21504
	ds_read_b128 v[210:213], v153 offset:22528
	ds_read_b128 v[214:217], v153 offset:23552
	s_waitcnt vmcnt(8)
	s_waitcnt lgkmcnt(0)
	s_barrier
	s_waitcnt lgkmcnt(0)
	s_setprio 1
	v_mfma_f32_16x16x32_bf16 v[60:63], v[154:157], v[186:189], v[60:63]
	v_mfma_f32_16x16x32_bf16 v[60:63], v[158:161], v[190:193], v[60:63]
	v_mfma_f32_16x16x32_bf16 v[56:59], v[166:169], v[190:193], v[56:59]
	v_mfma_f32_16x16x32_bf16 v[56:59], v[162:165], v[186:189], v[56:59]
	v_mfma_f32_16x16x32_bf16 v[52:55], v[170:173], v[186:189], v[52:55]
	v_mfma_f32_16x16x32_bf16 v[52:55], v[174:177], v[190:193], v[52:55]
	v_mfma_f32_16x16x32_bf16 v[48:51], v[182:185], v[190:193], v[48:51]
	v_mfma_f32_16x16x32_bf16 v[48:51], v[178:181], v[186:189], v[48:51]
	v_mfma_f32_16x16x32_bf16 v[32:35], v[178:181], v[194:197], v[32:35]
	v_mfma_f32_16x16x32_bf16 v[32:35], v[182:185], v[198:201], v[32:35]
	v_mfma_f32_16x16x32_bf16 v[36:39], v[174:177], v[198:201], v[36:39]
	v_mfma_f32_16x16x32_bf16 v[36:39], v[170:173], v[194:197], v[36:39]
	v_mfma_f32_16x16x32_bf16 v[40:43], v[162:165], v[194:197], v[40:43]
	v_mfma_f32_16x16x32_bf16 v[40:43], v[166:169], v[198:201], v[40:43]
	v_mfma_f32_16x16x32_bf16 v[44:47], v[158:161], v[198:201], v[44:47]
	v_mfma_f32_16x16x32_bf16 v[44:47], v[154:157], v[194:197], v[44:47]
	v_mfma_f32_16x16x32_bf16 v[28:31], v[154:157], v[202:205], v[28:31]
	v_mfma_f32_16x16x32_bf16 v[28:31], v[158:161], v[206:209], v[28:31]
	v_mfma_f32_16x16x32_bf16 v[24:27], v[166:169], v[206:209], v[24:27]
	v_mfma_f32_16x16x32_bf16 v[24:27], v[162:165], v[202:205], v[24:27]
	v_mfma_f32_16x16x32_bf16 v[20:23], v[170:173], v[202:205], v[20:23]
	v_mfma_f32_16x16x32_bf16 v[20:23], v[174:177], v[206:209], v[20:23]
	v_mfma_f32_16x16x32_bf16 v[16:19], v[182:185], v[206:209], v[16:19]
	v_mfma_f32_16x16x32_bf16 v[16:19], v[178:181], v[202:205], v[16:19]
	v_mfma_f32_16x16x32_bf16 v[0:3], v[178:181], v[210:213], v[0:3]
	v_mfma_f32_16x16x32_bf16 v[0:3], v[182:185], v[214:217], v[0:3]
	v_mfma_f32_16x16x32_bf16 v[4:7], v[174:177], v[214:217], v[4:7]
	v_mfma_f32_16x16x32_bf16 v[4:7], v[170:173], v[210:213], v[4:7]
	v_mfma_f32_16x16x32_bf16 v[8:11], v[162:165], v[210:213], v[8:11]
	v_mfma_f32_16x16x32_bf16 v[8:11], v[166:169], v[214:217], v[8:11]
	v_mfma_f32_16x16x32_bf16 v[12:15], v[158:161], v[214:217], v[12:15]
	v_mfma_f32_16x16x32_bf16 v[12:15], v[154:157], v[210:213], v[12:15]
	s_setprio 0
	s_barrier
	s_add_i32 s59, 0, 0x18000
	s_add_i32 s60, 0, 0x1c000
	v_add_u32_e32 v166, s59, v152
	v_add_u32_e32 v182, s60, v152
	ds_read_b128 v[154:157], v166
	ds_read_b128 v[158:161], v166 offset:1024
	ds_read_b128 v[162:165], v166 offset:2048
	ds_read_b128 v[166:169], v166 offset:3072
	ds_read_b128 v[170:173], v182
	ds_read_b128 v[174:177], v182 offset:1024
	ds_read_b128 v[178:181], v182 offset:2048
	ds_read_b128 v[182:185], v182 offset:3072
	s_add_u32 s34, s34, 0x100000
	s_addc_u32 s35, s35, 0
	s_mov_b32 m0, s46
	v_lshl_add_u64 v[186:187], s[34:35], 0, v[128:129]
	global_load_lds_dwordx4 v[186:187], off
	v_lshl_add_u64 v[186:187], s[34:35], 0, v[132:133]
	s_mov_b32 m0, s47
	s_nop 0
	global_load_lds_dwordx4 v[186:187], off
	ds_read_b128 v[186:189], v153 offset:32768
	ds_read_b128 v[190:193], v153 offset:33792
	ds_read_b128 v[194:197], v153 offset:34816
	ds_read_b128 v[198:201], v153 offset:35840
	ds_read_b128 v[202:205], v153 offset:36864
	ds_read_b128 v[206:209], v153 offset:37888
	ds_read_b128 v[210:213], v153 offset:38912
	ds_read_b128 v[214:217], v153 offset:39936
	s_waitcnt vmcnt(8)
	s_waitcnt lgkmcnt(0)
	s_barrier
	s_waitcnt lgkmcnt(0)
	s_setprio 1
	v_mfma_f32_16x16x32_bf16 v[124:127], v[154:157], v[186:189], v[124:127]
	v_mfma_f32_16x16x32_bf16 v[124:127], v[158:161], v[190:193], v[124:127]
	v_mfma_f32_16x16x32_bf16 v[120:123], v[166:169], v[190:193], v[120:123]
	v_mfma_f32_16x16x32_bf16 v[120:123], v[162:165], v[186:189], v[120:123]
	v_mfma_f32_16x16x32_bf16 v[116:119], v[170:173], v[186:189], v[116:119]
	v_mfma_f32_16x16x32_bf16 v[116:119], v[174:177], v[190:193], v[116:119]
	v_mfma_f32_16x16x32_bf16 v[112:115], v[182:185], v[190:193], v[112:115]
	v_mfma_f32_16x16x32_bf16 v[112:115], v[178:181], v[186:189], v[112:115]
	v_mfma_f32_16x16x32_bf16 v[96:99], v[178:181], v[194:197], v[96:99]
	v_mfma_f32_16x16x32_bf16 v[96:99], v[182:185], v[198:201], v[96:99]
	v_mfma_f32_16x16x32_bf16 v[100:103], v[174:177], v[198:201], v[100:103]
	v_mfma_f32_16x16x32_bf16 v[100:103], v[170:173], v[194:197], v[100:103]
	v_mfma_f32_16x16x32_bf16 v[104:107], v[162:165], v[194:197], v[104:107]
	v_mfma_f32_16x16x32_bf16 v[104:107], v[166:169], v[198:201], v[104:107]
	v_mfma_f32_16x16x32_bf16 v[108:111], v[158:161], v[198:201], v[108:111]
	v_mfma_f32_16x16x32_bf16 v[108:111], v[154:157], v[194:197], v[108:111]
	v_mfma_f32_16x16x32_bf16 v[92:95], v[154:157], v[202:205], v[92:95]
	v_mfma_f32_16x16x32_bf16 v[92:95], v[158:161], v[206:209], v[92:95]
	v_mfma_f32_16x16x32_bf16 v[88:91], v[166:169], v[206:209], v[88:91]
	v_mfma_f32_16x16x32_bf16 v[88:91], v[162:165], v[202:205], v[88:91]
	v_mfma_f32_16x16x32_bf16 v[84:87], v[170:173], v[202:205], v[84:87]
	v_mfma_f32_16x16x32_bf16 v[84:87], v[174:177], v[206:209], v[84:87]
	v_mfma_f32_16x16x32_bf16 v[80:83], v[182:185], v[206:209], v[80:83]
	v_mfma_f32_16x16x32_bf16 v[80:83], v[178:181], v[202:205], v[80:83]
	v_mfma_f32_16x16x32_bf16 v[64:67], v[178:181], v[210:213], v[64:67]
	v_mfma_f32_16x16x32_bf16 v[64:67], v[182:185], v[214:217], v[64:67]
	v_mfma_f32_16x16x32_bf16 v[68:71], v[174:177], v[214:217], v[68:71]
	v_mfma_f32_16x16x32_bf16 v[68:71], v[170:173], v[210:213], v[68:71]
	v_mfma_f32_16x16x32_bf16 v[72:75], v[162:165], v[210:213], v[72:75]
	v_mfma_f32_16x16x32_bf16 v[72:75], v[166:169], v[214:217], v[72:75]
	v_mfma_f32_16x16x32_bf16 v[76:79], v[158:161], v[214:217], v[76:79]
	v_mfma_f32_16x16x32_bf16 v[76:79], v[154:157], v[210:213], v[76:79]
	s_setprio 0
	s_barrier
	s_add_i32 s34, s59, s43
	v_lshl_add_u64 v[186:187], v[218:219], 0, s[14:15]
	s_mov_b32 m0, s34
	s_nop 0
	global_load_lds_dwordx4 v[186:187], off
	s_add_i32 m0, s34, 0x2000
	s_add_u32 s30, s30, 0x100080
	v_lshl_add_u64 v[186:187], v[220:221], 0, s[14:15]
	s_addc_u32 s31, s31, 0
	s_add_i32 s34, s60, s43
	global_load_lds_dwordx4 v[186:187], off
	v_lshl_add_u64 v[186:187], s[30:31], 0, v[130:131]
	s_mov_b32 m0, s34
	s_nop 0
	global_load_lds_dwordx4 v[186:187], off
	v_lshl_add_u64 v[186:187], s[30:31], 0, v[134:135]
	s_add_i32 m0, s34, 0x2000
	s_nop 0
	global_load_lds_dwordx4 v[186:187], off
	v_lshl_add_u64 v[186:187], v[222:223], 0, s[16:17]
	s_mov_b32 m0, s49
	s_nop 0
	global_load_lds_dwordx4 v[186:187], off
	v_lshl_add_u64 v[186:187], v[224:225], 0, s[16:17]
	s_mov_b32 m0, s50
	s_nop 0
	global_load_lds_dwordx4 v[186:187], off
	ds_read_b128 v[186:189], v153 offset:49152
	ds_read_b128 v[190:193], v153 offset:50176
	ds_read_b128 v[194:197], v153 offset:51200
	ds_read_b128 v[198:201], v153 offset:52224
	ds_read_b128 v[202:205], v153 offset:53248
	ds_read_b128 v[206:209], v153 offset:54272
	ds_read_b128 v[210:213], v153 offset:55296
	ds_read_b128 v[214:217], v153 offset:56320
	s_waitcnt vmcnt(8)
	s_waitcnt lgkmcnt(0)
	s_barrier
	s_waitcnt lgkmcnt(0)
	s_setprio 1
	v_mfma_f32_16x16x32_bf16 v[60:63], v[154:157], v[186:189], v[60:63]
	v_mfma_f32_16x16x32_bf16 v[60:63], v[158:161], v[190:193], v[60:63]
	v_mfma_f32_16x16x32_bf16 v[56:59], v[166:169], v[190:193], v[56:59]
	v_mfma_f32_16x16x32_bf16 v[56:59], v[162:165], v[186:189], v[56:59]
	v_mfma_f32_16x16x32_bf16 v[52:55], v[170:173], v[186:189], v[52:55]
	v_mfma_f32_16x16x32_bf16 v[52:55], v[174:177], v[190:193], v[52:55]
	v_mfma_f32_16x16x32_bf16 v[48:51], v[182:185], v[190:193], v[48:51]
	v_mfma_f32_16x16x32_bf16 v[48:51], v[178:181], v[186:189], v[48:51]
	v_mfma_f32_16x16x32_bf16 v[32:35], v[178:181], v[194:197], v[32:35]
	v_mfma_f32_16x16x32_bf16 v[32:35], v[182:185], v[198:201], v[32:35]
	v_mfma_f32_16x16x32_bf16 v[36:39], v[174:177], v[198:201], v[36:39]
	v_mfma_f32_16x16x32_bf16 v[36:39], v[170:173], v[194:197], v[36:39]
	v_mfma_f32_16x16x32_bf16 v[40:43], v[162:165], v[194:197], v[40:43]
	v_mfma_f32_16x16x32_bf16 v[40:43], v[166:169], v[198:201], v[40:43]
	v_mfma_f32_16x16x32_bf16 v[44:47], v[158:161], v[198:201], v[44:47]
	v_mfma_f32_16x16x32_bf16 v[44:47], v[154:157], v[194:197], v[44:47]
	v_mfma_f32_16x16x32_bf16 v[28:31], v[154:157], v[202:205], v[28:31]
	v_mfma_f32_16x16x32_bf16 v[28:31], v[158:161], v[206:209], v[28:31]
	v_mfma_f32_16x16x32_bf16 v[24:27], v[166:169], v[206:209], v[24:27]
	v_mfma_f32_16x16x32_bf16 v[24:27], v[162:165], v[202:205], v[24:27]
	v_mfma_f32_16x16x32_bf16 v[20:23], v[170:173], v[202:205], v[20:23]
	v_mfma_f32_16x16x32_bf16 v[20:23], v[174:177], v[206:209], v[20:23]
	v_mfma_f32_16x16x32_bf16 v[16:19], v[182:185], v[206:209], v[16:19]
	v_mfma_f32_16x16x32_bf16 v[16:19], v[178:181], v[202:205], v[16:19]
	v_mfma_f32_16x16x32_bf16 v[0:3], v[178:181], v[210:213], v[0:3]
	v_mfma_f32_16x16x32_bf16 v[0:3], v[182:185], v[214:217], v[0:3]
	v_mfma_f32_16x16x32_bf16 v[4:7], v[174:177], v[214:217], v[4:7]
	v_mfma_f32_16x16x32_bf16 v[4:7], v[170:173], v[210:213], v[4:7]
	v_mfma_f32_16x16x32_bf16 v[8:11], v[162:165], v[210:213], v[8:11]
	v_mfma_f32_16x16x32_bf16 v[8:11], v[166:169], v[214:217], v[8:11]
	v_mfma_f32_16x16x32_bf16 v[12:15], v[158:161], v[214:217], v[12:15]
	v_mfma_f32_16x16x32_bf16 v[12:15], v[154:157], v[210:213], v[12:15]
	s_setprio 0
	s_barrier
	s_add_i32 s58, s58, 2
	s_add_u32 s56, s56, 0x100
	s_addc_u32 s57, s57, 0
	s_add_u32 s28, s28, 0x1000
	s_addc_u32 s29, s29, 0
	v_lshl_add_u64 v[146:147], v[146:147], 0, s[18:19]
	s_cmp_gt_u32 s58, 61
	v_lshl_add_u64 v[144:145], v[144:145], 0, s[18:19]
	s_cbranch_scc0 .LBB0_1340
	s_andn2_b64 vcc, exec, s[4:5]
	s_cbranch_vccnz .LBB0_1332
	v_mov_b32_e32 v0, 0
	s_mov_b32 s7, s20
	s_mov_b32 s6, s22
	s_mov_b64 s[8:9], s[26:27]
	s_mov_b64 s[10:11], s[24:25]
	s_mov_b32 s48, s53
	v_mov_b32_e32 v1, v0
	v_mov_b32_e32 v2, v0
	v_mov_b32_e32 v3, v0
	v_mov_b32_e32 v4, v0
	v_mov_b32_e32 v5, v0
	v_mov_b32_e32 v6, v0
	v_mov_b32_e32 v7, v0
	v_mov_b32_e32 v16, v0
	v_mov_b32_e32 v17, v0
	v_mov_b32_e32 v18, v0
	v_mov_b32_e32 v19, v0
	v_mov_b32_e32 v20, v0
	v_mov_b32_e32 v21, v0
	v_mov_b32_e32 v22, v0
	v_mov_b32_e32 v23, v0
	v_mov_b32_e32 v32, v0
	v_mov_b32_e32 v33, v0
	v_mov_b32_e32 v34, v0
	v_mov_b32_e32 v35, v0
	v_mov_b32_e32 v36, v0
	v_mov_b32_e32 v37, v0
	v_mov_b32_e32 v38, v0
	v_mov_b32_e32 v39, v0
	v_mov_b32_e32 v48, v0
	v_mov_b32_e32 v49, v0
	v_mov_b32_e32 v50, v0
	v_mov_b32_e32 v51, v0
	v_mov_b32_e32 v52, v0
	v_mov_b32_e32 v53, v0
	v_mov_b32_e32 v54, v0
	v_mov_b32_e32 v55, v0
	v_mov_b32_e32 v8, v0
	v_mov_b32_e32 v9, v0
	v_mov_b32_e32 v10, v0
	v_mov_b32_e32 v11, v0
	v_mov_b32_e32 v12, v0
	v_mov_b32_e32 v13, v0
	v_mov_b32_e32 v14, v0
	v_mov_b32_e32 v15, v0
	v_mov_b32_e32 v24, v0
	v_mov_b32_e32 v25, v0
	v_mov_b32_e32 v26, v0
	v_mov_b32_e32 v27, v0
	v_mov_b32_e32 v28, v0
	v_mov_b32_e32 v29, v0
	v_mov_b32_e32 v30, v0
	v_mov_b32_e32 v31, v0
	v_mov_b32_e32 v40, v0
	v_mov_b32_e32 v41, v0
	v_mov_b32_e32 v42, v0
	v_mov_b32_e32 v43, v0
	v_mov_b32_e32 v44, v0
	v_mov_b32_e32 v45, v0
	v_mov_b32_e32 v46, v0
	v_mov_b32_e32 v47, v0
	v_mov_b32_e32 v56, v0
	v_mov_b32_e32 v57, v0
	v_mov_b32_e32 v58, v0
	v_mov_b32_e32 v59, v0
	v_mov_b32_e32 v60, v0
	v_mov_b32_e32 v61, v0
	v_mov_b32_e32 v62, v0
	v_mov_b32_e32 v63, v0
	v_mov_b32_e32 v64, v0
	v_mov_b32_e32 v65, v0
	v_mov_b32_e32 v66, v0
	v_mov_b32_e32 v67, v0
	v_mov_b32_e32 v68, v0
	v_mov_b32_e32 v69, v0
	v_mov_b32_e32 v70, v0
	v_mov_b32_e32 v71, v0
	v_mov_b32_e32 v80, v0
	v_mov_b32_e32 v81, v0
	v_mov_b32_e32 v82, v0
	v_mov_b32_e32 v83, v0
	v_mov_b32_e32 v84, v0
	v_mov_b32_e32 v85, v0
	v_mov_b32_e32 v86, v0
	v_mov_b32_e32 v87, v0
	v_mov_b32_e32 v96, v0
	v_mov_b32_e32 v97, v0
	v_mov_b32_e32 v98, v0
	v_mov_b32_e32 v99, v0
	v_mov_b32_e32 v100, v0
	v_mov_b32_e32 v101, v0
	v_mov_b32_e32 v102, v0
	v_mov_b32_e32 v103, v0
	v_mov_b32_e32 v112, v0
	v_mov_b32_e32 v113, v0
	v_mov_b32_e32 v114, v0
	v_mov_b32_e32 v115, v0
	v_mov_b32_e32 v116, v0
	v_mov_b32_e32 v117, v0
	v_mov_b32_e32 v118, v0
	v_mov_b32_e32 v119, v0
	v_mov_b32_e32 v72, v0
	v_mov_b32_e32 v73, v0
	v_mov_b32_e32 v74, v0
	v_mov_b32_e32 v75, v0
	v_mov_b32_e32 v76, v0
	v_mov_b32_e32 v77, v0
	v_mov_b32_e32 v78, v0
	v_mov_b32_e32 v79, v0
	v_mov_b32_e32 v88, v0
	v_mov_b32_e32 v89, v0
	v_mov_b32_e32 v90, v0
	v_mov_b32_e32 v91, v0
	v_mov_b32_e32 v92, v0
	v_mov_b32_e32 v93, v0
	v_mov_b32_e32 v94, v0
	v_mov_b32_e32 v95, v0
	v_mov_b32_e32 v104, v0
	v_mov_b32_e32 v105, v0
	v_mov_b32_e32 v106, v0
	v_mov_b32_e32 v107, v0
	v_mov_b32_e32 v108, v0
	v_mov_b32_e32 v109, v0
	v_mov_b32_e32 v110, v0
	v_mov_b32_e32 v111, v0
	v_mov_b32_e32 v120, v0
	v_mov_b32_e32 v121, v0
	v_mov_b32_e32 v122, v0
	v_mov_b32_e32 v123, v0
	v_mov_b32_e32 v124, v0
	v_mov_b32_e32 v125, v0
	v_mov_b32_e32 v126, v0
	v_mov_b32_e32 v127, v0
	s_branch .LBB0_1332

.LBB0_1435:
	ds_read_b128 v[128:131], v180
	ds_read_b128 v[132:135], v180 offset:1024
	ds_read_b128 v[136:139], v180 offset:2048
	ds_read_b128 v[140:143], v180 offset:3072
	ds_read_b128 v[144:147], v181
	ds_read_b128 v[148:151], v181 offset:1024
	ds_read_b128 v[170:173], v181 offset:2048
	ds_read_b128 v[174:177], v181 offset:3072
	s_add_u32 s26, s24, 0xfffc0080
	s_addc_u32 s27, s25, -1
	s_cmp_eq_u32 s35, 12
	s_cselect_b32 s29, s1, s27
	s_cselect_b32 s28, s19, s26
	s_cselect_b32 s27, s17, s34
	s_cselect_b32 s26, s30, s31
	v_lshl_add_u64 v[184:185], s[24:25], 0, v[162:163]
	s_add_i32 m0, s40, 0xc000
	s_nop 0
	global_load_lds_dwordx4 v[184:185], off
	v_lshl_add_u64 v[184:185], s[24:25], 0, v[164:165]
	s_add_i32 m0, s40, 0xe000
	s_nop 0
	global_load_lds_dwordx4 v[184:185], off
	ds_read_b128 v[184:187], v182
	ds_read_b128 v[188:191], v182 offset:1024
	ds_read_b128 v[192:195], v182 offset:2048
	ds_read_b128 v[196:199], v182 offset:3072
	ds_read_b128 v[200:203], v182 offset:4096
	ds_read_b128 v[204:207], v182 offset:5120
	ds_read_b128 v[208:211], v182 offset:6144
	ds_read_b128 v[212:215], v182 offset:7168
	s_waitcnt vmcnt(8)
	s_waitcnt lgkmcnt(0)
	s_barrier
	s_waitcnt lgkmcnt(0)
	s_setprio 1
	v_mfma_f32_16x16x32_bf16 v[124:127], v[128:131], v[184:187], v[124:127]
	v_mfma_f32_16x16x32_bf16 v[124:127], v[132:135], v[188:191], v[124:127]
	v_mfma_f32_16x16x32_bf16 v[120:123], v[140:143], v[188:191], v[120:123]
	v_mfma_f32_16x16x32_bf16 v[120:123], v[136:139], v[184:187], v[120:123]
	v_mfma_f32_16x16x32_bf16 v[116:119], v[144:147], v[184:187], v[116:119]
	v_mfma_f32_16x16x32_bf16 v[116:119], v[148:151], v[188:191], v[116:119]
	v_mfma_f32_16x16x32_bf16 v[112:115], v[174:177], v[188:191], v[112:115]
	v_mfma_f32_16x16x32_bf16 v[112:115], v[170:173], v[184:187], v[112:115]
	v_mfma_f32_16x16x32_bf16 v[96:99], v[170:173], v[192:195], v[96:99]
	v_mfma_f32_16x16x32_bf16 v[96:99], v[174:177], v[196:199], v[96:99]
	v_mfma_f32_16x16x32_bf16 v[100:103], v[148:151], v[196:199], v[100:103]
	v_mfma_f32_16x16x32_bf16 v[100:103], v[144:147], v[192:195], v[100:103]
	v_mfma_f32_16x16x32_bf16 v[104:107], v[136:139], v[192:195], v[104:107]
	v_mfma_f32_16x16x32_bf16 v[104:107], v[140:143], v[196:199], v[104:107]
	v_mfma_f32_16x16x32_bf16 v[108:111], v[132:135], v[196:199], v[108:111]
	v_mfma_f32_16x16x32_bf16 v[108:111], v[128:131], v[192:195], v[108:111]
	v_mfma_f32_16x16x32_bf16 v[92:95], v[128:131], v[200:203], v[92:95]
	v_mfma_f32_16x16x32_bf16 v[92:95], v[132:135], v[204:207], v[92:95]
	v_mfma_f32_16x16x32_bf16 v[88:91], v[140:143], v[204:207], v[88:91]
	v_mfma_f32_16x16x32_bf16 v[88:91], v[136:139], v[200:203], v[88:91]
	v_mfma_f32_16x16x32_bf16 v[84:87], v[144:147], v[200:203], v[84:87]
	v_mfma_f32_16x16x32_bf16 v[84:87], v[148:151], v[204:207], v[84:87]
	v_mfma_f32_16x16x32_bf16 v[80:83], v[174:177], v[204:207], v[80:83]
	v_mfma_f32_16x16x32_bf16 v[80:83], v[170:173], v[200:203], v[80:83]
	v_mfma_f32_16x16x32_bf16 v[64:67], v[170:173], v[208:211], v[64:67]
	v_mfma_f32_16x16x32_bf16 v[64:67], v[174:177], v[212:215], v[64:67]
	v_mfma_f32_16x16x32_bf16 v[68:71], v[148:151], v[212:215], v[68:71]
	v_mfma_f32_16x16x32_bf16 v[68:71], v[144:147], v[208:211], v[68:71]
	v_mfma_f32_16x16x32_bf16 v[72:75], v[136:139], v[208:211], v[72:75]
	v_mfma_f32_16x16x32_bf16 v[72:75], v[140:143], v[212:215], v[72:75]
	v_mfma_f32_16x16x32_bf16 v[76:79], v[132:135], v[212:215], v[76:79]
	v_mfma_f32_16x16x32_bf16 v[76:79], v[128:131], v[208:211], v[76:79]
	s_setprio 0
	s_barrier
	s_add_i32 s54, s50, s39
	v_lshl_add_u64 v[216:217], s[26:27], 0, v[154:155]
	s_mov_b32 m0, s54
	v_lshl_add_u64 v[218:219], s[26:27], 0, v[158:159]
	global_load_lds_dwordx4 v[216:217], off
	s_add_i32 m0, s54, 0x2000
	s_add_u32 s54, s26, 0x100000
	s_addc_u32 s55, s27, 0
	s_add_i32 s56, s51, s39
	global_load_lds_dwordx4 v[218:219], off
	v_lshl_add_u64 v[184:185], s[54:55], 0, v[154:155]
	s_mov_b32 m0, s56
	v_lshl_add_u64 v[220:221], s[28:29], 0, v[152:153]
	global_load_lds_dwordx4 v[184:185], off
	v_lshl_add_u64 v[184:185], s[54:55], 0, v[158:159]
	s_add_i32 m0, s56, 0x2000
	v_lshl_add_u64 v[222:223], s[28:29], 0, v[156:157]
	global_load_lds_dwordx4 v[184:185], off
	s_mov_b32 m0, s40
	s_nop 0
	global_load_lds_dwordx4 v[220:221], off
	s_mov_b32 m0, s41
	s_nop 0
	global_load_lds_dwordx4 v[222:223], off
	ds_read_b128 v[184:187], v182 offset:16384
	ds_read_b128 v[188:191], v182 offset:17408
	ds_read_b128 v[192:195], v182 offset:18432
	ds_read_b128 v[196:199], v182 offset:19456
	ds_read_b128 v[200:203], v182 offset:20480
	ds_read_b128 v[204:207], v182 offset:21504
	ds_read_b128 v[208:211], v182 offset:22528
	ds_read_b128 v[212:215], v182 offset:23552
	s_waitcnt vmcnt(8)
	s_waitcnt lgkmcnt(0)
	s_barrier
	s_waitcnt lgkmcnt(0)
	s_setprio 1
	v_mfma_f32_16x16x32_bf16 v[60:63], v[128:131], v[184:187], v[60:63]
	v_mfma_f32_16x16x32_bf16 v[60:63], v[132:135], v[188:191], v[60:63]
	v_mfma_f32_16x16x32_bf16 v[56:59], v[140:143], v[188:191], v[56:59]
	v_mfma_f32_16x16x32_bf16 v[56:59], v[136:139], v[184:187], v[56:59]
	v_mfma_f32_16x16x32_bf16 v[52:55], v[144:147], v[184:187], v[52:55]
	v_mfma_f32_16x16x32_bf16 v[52:55], v[148:151], v[188:191], v[52:55]
	v_mfma_f32_16x16x32_bf16 v[48:51], v[174:177], v[188:191], v[48:51]
	v_mfma_f32_16x16x32_bf16 v[48:51], v[170:173], v[184:187], v[48:51]
	v_mfma_f32_16x16x32_bf16 v[32:35], v[170:173], v[192:195], v[32:35]
	v_mfma_f32_16x16x32_bf16 v[32:35], v[174:177], v[196:199], v[32:35]
	v_mfma_f32_16x16x32_bf16 v[36:39], v[148:151], v[196:199], v[36:39]
	v_mfma_f32_16x16x32_bf16 v[36:39], v[144:147], v[192:195], v[36:39]
	v_mfma_f32_16x16x32_bf16 v[40:43], v[136:139], v[192:195], v[40:43]
	v_mfma_f32_16x16x32_bf16 v[40:43], v[140:143], v[196:199], v[40:43]
	v_mfma_f32_16x16x32_bf16 v[44:47], v[132:135], v[196:199], v[44:47]
	v_mfma_f32_16x16x32_bf16 v[44:47], v[128:131], v[192:195], v[44:47]
	v_mfma_f32_16x16x32_bf16 v[28:31], v[128:131], v[200:203], v[28:31]
	v_mfma_f32_16x16x32_bf16 v[28:31], v[132:135], v[204:207], v[28:31]
	v_mfma_f32_16x16x32_bf16 v[24:27], v[140:143], v[204:207], v[24:27]
	v_mfma_f32_16x16x32_bf16 v[24:27], v[136:139], v[200:203], v[24:27]
	v_mfma_f32_16x16x32_bf16 v[20:23], v[144:147], v[200:203], v[20:23]
	v_mfma_f32_16x16x32_bf16 v[20:23], v[148:151], v[204:207], v[20:23]
	v_mfma_f32_16x16x32_bf16 v[16:19], v[174:177], v[204:207], v[16:19]
	v_mfma_f32_16x16x32_bf16 v[16:19], v[170:173], v[200:203], v[16:19]
	v_mfma_f32_16x16x32_bf16 v[0:3], v[170:173], v[208:211], v[0:3]
	v_mfma_f32_16x16x32_bf16 v[0:3], v[174:177], v[212:215], v[0:3]
	v_mfma_f32_16x16x32_bf16 v[4:7], v[148:151], v[212:215], v[4:7]
	v_mfma_f32_16x16x32_bf16 v[4:7], v[144:147], v[208:211], v[4:7]
	v_mfma_f32_16x16x32_bf16 v[8:11], v[136:139], v[208:211], v[8:11]
	v_mfma_f32_16x16x32_bf16 v[8:11], v[140:143], v[212:215], v[8:11]
	v_mfma_f32_16x16x32_bf16 v[12:15], v[132:135], v[212:215], v[12:15]
	v_mfma_f32_16x16x32_bf16 v[12:15], v[128:131], v[208:211], v[12:15]
	s_setprio 0
	s_barrier
	s_add_i32 s54, 0, 0x18000
	s_add_i32 s55, 0, 0x1c000
	v_add_u32_e32 v140, s54, v178
	v_add_u32_e32 v174, s55, v178
	ds_read_b128 v[128:131], v140
	ds_read_b128 v[132:135], v140 offset:1024
	ds_read_b128 v[136:139], v140 offset:2048
	ds_read_b128 v[140:143], v140 offset:3072
	ds_read_b128 v[144:147], v174
	ds_read_b128 v[148:151], v174 offset:1024
	ds_read_b128 v[170:173], v174 offset:2048
	ds_read_b128 v[174:177], v174 offset:3072
	s_add_u32 s28, s28, 0x40000
	s_addc_u32 s29, s29, 0
	s_mov_b32 m0, s42
	v_lshl_add_u64 v[184:185], s[28:29], 0, v[152:153]
	global_load_lds_dwordx4 v[184:185], off
	v_lshl_add_u64 v[184:185], s[28:29], 0, v[156:157]
	s_mov_b32 m0, s43
	s_nop 0
	global_load_lds_dwordx4 v[184:185], off
	ds_read_b128 v[184:187], v182 offset:32768
	ds_read_b128 v[188:191], v182 offset:33792
	ds_read_b128 v[192:195], v182 offset:34816
	ds_read_b128 v[196:199], v182 offset:35840
	ds_read_b128 v[200:203], v182 offset:36864
	ds_read_b128 v[204:207], v182 offset:37888
	ds_read_b128 v[208:211], v182 offset:38912
	ds_read_b128 v[212:215], v182 offset:39936
	s_waitcnt vmcnt(8)
	s_waitcnt lgkmcnt(0)
	s_barrier
	s_waitcnt lgkmcnt(0)
	s_setprio 1
	v_mfma_f32_16x16x32_bf16 v[124:127], v[128:131], v[184:187], v[124:127]
	v_mfma_f32_16x16x32_bf16 v[124:127], v[132:135], v[188:191], v[124:127]
	v_mfma_f32_16x16x32_bf16 v[120:123], v[140:143], v[188:191], v[120:123]
	v_mfma_f32_16x16x32_bf16 v[120:123], v[136:139], v[184:187], v[120:123]
	v_mfma_f32_16x16x32_bf16 v[116:119], v[144:147], v[184:187], v[116:119]
	v_mfma_f32_16x16x32_bf16 v[116:119], v[148:151], v[188:191], v[116:119]
	v_mfma_f32_16x16x32_bf16 v[112:115], v[174:177], v[188:191], v[112:115]
	v_mfma_f32_16x16x32_bf16 v[112:115], v[170:173], v[184:187], v[112:115]
	v_mfma_f32_16x16x32_bf16 v[96:99], v[170:173], v[192:195], v[96:99]
	v_mfma_f32_16x16x32_bf16 v[96:99], v[174:177], v[196:199], v[96:99]
	v_mfma_f32_16x16x32_bf16 v[100:103], v[148:151], v[196:199], v[100:103]
	v_mfma_f32_16x16x32_bf16 v[100:103], v[144:147], v[192:195], v[100:103]
	v_mfma_f32_16x16x32_bf16 v[104:107], v[136:139], v[192:195], v[104:107]
	v_mfma_f32_16x16x32_bf16 v[104:107], v[140:143], v[196:199], v[104:107]
	v_mfma_f32_16x16x32_bf16 v[108:111], v[132:135], v[196:199], v[108:111]
	v_mfma_f32_16x16x32_bf16 v[108:111], v[128:131], v[192:195], v[108:111]
	v_mfma_f32_16x16x32_bf16 v[92:95], v[128:131], v[200:203], v[92:95]
	v_mfma_f32_16x16x32_bf16 v[92:95], v[132:135], v[204:207], v[92:95]
	v_mfma_f32_16x16x32_bf16 v[88:91], v[140:143], v[204:207], v[88:91]
	v_mfma_f32_16x16x32_bf16 v[88:91], v[136:139], v[200:203], v[88:91]
	v_mfma_f32_16x16x32_bf16 v[84:87], v[144:147], v[200:203], v[84:87]
	v_mfma_f32_16x16x32_bf16 v[84:87], v[148:151], v[204:207], v[84:87]
	v_mfma_f32_16x16x32_bf16 v[80:83], v[174:177], v[204:207], v[80:83]
	v_mfma_f32_16x16x32_bf16 v[80:83], v[170:173], v[200:203], v[80:83]
	v_mfma_f32_16x16x32_bf16 v[64:67], v[170:173], v[208:211], v[64:67]
	v_mfma_f32_16x16x32_bf16 v[64:67], v[174:177], v[212:215], v[64:67]
	v_mfma_f32_16x16x32_bf16 v[68:71], v[148:151], v[212:215], v[68:71]
	v_mfma_f32_16x16x32_bf16 v[68:71], v[144:147], v[208:211], v[68:71]
	v_mfma_f32_16x16x32_bf16 v[72:75], v[136:139], v[208:211], v[72:75]
	v_mfma_f32_16x16x32_bf16 v[72:75], v[140:143], v[212:215], v[72:75]
	v_mfma_f32_16x16x32_bf16 v[76:79], v[132:135], v[212:215], v[76:79]
	v_mfma_f32_16x16x32_bf16 v[76:79], v[128:131], v[208:211], v[76:79]
	s_setprio 0
	s_barrier
	s_add_i32 s28, s54, s39
	v_lshl_add_u64 v[184:185], v[216:217], 0, s[14:15]
	s_mov_b32 m0, s28
	s_nop 0
	global_load_lds_dwordx4 v[184:185], off
	s_add_i32 m0, s28, 0x2000
	s_add_u32 s26, s26, 0x100080
	v_lshl_add_u64 v[184:185], v[218:219], 0, s[14:15]
	s_addc_u32 s27, s27, 0
	s_add_i32 s28, s55, s39
	global_load_lds_dwordx4 v[184:185], off
	v_lshl_add_u64 v[184:185], s[26:27], 0, v[154:155]
	s_mov_b32 m0, s28
	s_nop 0
	global_load_lds_dwordx4 v[184:185], off
	v_lshl_add_u64 v[184:185], s[26:27], 0, v[158:159]
	s_add_i32 m0, s28, 0x2000
	s_nop 0
	global_load_lds_dwordx4 v[184:185], off
	v_lshl_add_u64 v[184:185], v[220:221], 0, s[14:15]
	s_mov_b32 m0, s45
	s_nop 0
	global_load_lds_dwordx4 v[184:185], off
	v_lshl_add_u64 v[184:185], v[222:223], 0, s[14:15]
	s_mov_b32 m0, s46
	s_nop 0
	global_load_lds_dwordx4 v[184:185], off
	ds_read_b128 v[184:187], v182 offset:49152
	ds_read_b128 v[188:191], v182 offset:50176
	ds_read_b128 v[192:195], v182 offset:51200
	ds_read_b128 v[196:199], v182 offset:52224
	ds_read_b128 v[200:203], v182 offset:53248
	ds_read_b128 v[204:207], v182 offset:54272
	ds_read_b128 v[208:211], v182 offset:55296
	ds_read_b128 v[212:215], v182 offset:56320
	s_waitcnt vmcnt(8)
	s_waitcnt lgkmcnt(0)
	s_barrier
	s_waitcnt lgkmcnt(0)
	s_setprio 1
	v_mfma_f32_16x16x32_bf16 v[60:63], v[128:131], v[184:187], v[60:63]
	v_mfma_f32_16x16x32_bf16 v[60:63], v[132:135], v[188:191], v[60:63]
	v_mfma_f32_16x16x32_bf16 v[56:59], v[140:143], v[188:191], v[56:59]
	v_mfma_f32_16x16x32_bf16 v[56:59], v[136:139], v[184:187], v[56:59]
	v_mfma_f32_16x16x32_bf16 v[52:55], v[144:147], v[184:187], v[52:55]
	v_mfma_f32_16x16x32_bf16 v[52:55], v[148:151], v[188:191], v[52:55]
	v_mfma_f32_16x16x32_bf16 v[48:51], v[174:177], v[188:191], v[48:51]
	v_mfma_f32_16x16x32_bf16 v[48:51], v[170:173], v[184:187], v[48:51]
	v_mfma_f32_16x16x32_bf16 v[32:35], v[170:173], v[192:195], v[32:35]
	v_mfma_f32_16x16x32_bf16 v[32:35], v[174:177], v[196:199], v[32:35]
	v_mfma_f32_16x16x32_bf16 v[36:39], v[148:151], v[196:199], v[36:39]
	v_mfma_f32_16x16x32_bf16 v[36:39], v[144:147], v[192:195], v[36:39]
	v_mfma_f32_16x16x32_bf16 v[40:43], v[136:139], v[192:195], v[40:43]
	v_mfma_f32_16x16x32_bf16 v[40:43], v[140:143], v[196:199], v[40:43]
	v_mfma_f32_16x16x32_bf16 v[44:47], v[132:135], v[196:199], v[44:47]
	v_mfma_f32_16x16x32_bf16 v[44:47], v[128:131], v[192:195], v[44:47]
	v_mfma_f32_16x16x32_bf16 v[28:31], v[128:131], v[200:203], v[28:31]
	v_mfma_f32_16x16x32_bf16 v[28:31], v[132:135], v[204:207], v[28:31]
	v_mfma_f32_16x16x32_bf16 v[24:27], v[140:143], v[204:207], v[24:27]
	v_mfma_f32_16x16x32_bf16 v[24:27], v[136:139], v[200:203], v[24:27]
	v_mfma_f32_16x16x32_bf16 v[20:23], v[144:147], v[200:203], v[20:23]
	v_mfma_f32_16x16x32_bf16 v[20:23], v[148:151], v[204:207], v[20:23]
	v_mfma_f32_16x16x32_bf16 v[16:19], v[174:177], v[204:207], v[16:19]
	v_mfma_f32_16x16x32_bf16 v[16:19], v[170:173], v[200:203], v[16:19]
	v_mfma_f32_16x16x32_bf16 v[0:3], v[170:173], v[208:211], v[0:3]
	v_mfma_f32_16x16x32_bf16 v[0:3], v[174:177], v[212:215], v[0:3]
	v_mfma_f32_16x16x32_bf16 v[4:7], v[148:151], v[212:215], v[4:7]
	v_mfma_f32_16x16x32_bf16 v[4:7], v[144:147], v[208:211], v[4:7]
	v_mfma_f32_16x16x32_bf16 v[8:11], v[136:139], v[208:211], v[8:11]
	v_mfma_f32_16x16x32_bf16 v[8:11], v[140:143], v[212:215], v[8:11]
	v_mfma_f32_16x16x32_bf16 v[12:15], v[132:135], v[212:215], v[12:15]
	v_mfma_f32_16x16x32_bf16 v[12:15], v[128:131], v[208:211], v[12:15]
	s_setprio 0
	s_barrier
	s_add_i32 s35, s35, 2
	s_add_u32 s24, s24, 0x100
	s_addc_u32 s25, s25, 0
	s_add_u32 s31, s31, 0x100
	s_addc_u32 s34, s34, 0
	s_cmp_gt_u32 s35, 13
	s_cbranch_scc0 .LBB0_1435
	s_and_b64 vcc, exec, s[8:9]
	s_cbranch_vccz .LBB0_1438
	s_barrier

.LBB0_1543:
	ds_read_b128 v[128:131], v167
	ds_read_b128 v[154:157], v167 offset:1024
	ds_read_b128 v[172:175], v167 offset:2048
	ds_read_b128 v[176:179], v167 offset:3072
	ds_read_b128 v[180:183], v168
	ds_read_b128 v[184:187], v168 offset:1024
	ds_read_b128 v[188:191], v168 offset:2048
	ds_read_b128 v[192:195], v168 offset:3072
	s_add_u32 s22, s20, 0x1000
	s_addc_u32 s23, s21, 0
	s_cmp_eq_u32 s54, 60
	s_cselect_b32 s27, s13, s23
	s_cselect_b32 s26, s50, s22
	s_cselect_b32 s25, s11, s53
	s_cselect_b32 s24, s51, s52
	v_lshl_add_u64 v[160:161], s[20:21], 0, v[144:145]
	s_add_i32 m0, s19, 0xc000
	s_nop 0
	global_load_lds_dwordx4 v[160:161], off
	v_lshl_add_u64 v[160:161], s[20:21], 0, v[146:147]
	s_add_i32 m0, s19, 0xe000
	s_nop 0
	global_load_lds_dwordx4 v[160:161], off
	ds_read_b128 v[196:199], v169
	ds_read_b128 v[200:203], v169 offset:1024
	ds_read_b128 v[204:207], v169 offset:2048
	ds_read_b128 v[208:211], v169 offset:3072
	ds_read_b128 v[212:215], v169 offset:4096
	ds_read_b128 v[216:219], v169 offset:5120
	ds_read_b128 v[220:223], v169 offset:6144
	ds_read_b128 v[224:227], v169 offset:7168
	s_waitcnt vmcnt(8)
	s_waitcnt lgkmcnt(0)
	s_barrier
	s_waitcnt lgkmcnt(0)
	s_setprio 1
	v_mfma_f32_16x16x32_bf16 v[124:127], v[128:131], v[196:199], v[124:127]
	v_mfma_f32_16x16x32_bf16 v[124:127], v[154:157], v[200:203], v[124:127]
	v_mfma_f32_16x16x32_bf16 v[120:123], v[176:179], v[200:203], v[120:123]
	v_mfma_f32_16x16x32_bf16 v[120:123], v[172:175], v[196:199], v[120:123]
	v_mfma_f32_16x16x32_bf16 v[116:119], v[180:183], v[196:199], v[116:119]
	v_mfma_f32_16x16x32_bf16 v[116:119], v[184:187], v[200:203], v[116:119]
	v_mfma_f32_16x16x32_bf16 v[112:115], v[192:195], v[200:203], v[112:115]
	v_mfma_f32_16x16x32_bf16 v[112:115], v[188:191], v[196:199], v[112:115]
	v_mfma_f32_16x16x32_bf16 v[96:99], v[188:191], v[204:207], v[96:99]
	v_mfma_f32_16x16x32_bf16 v[96:99], v[192:195], v[208:211], v[96:99]
	v_mfma_f32_16x16x32_bf16 v[100:103], v[184:187], v[208:211], v[100:103]
	v_mfma_f32_16x16x32_bf16 v[100:103], v[180:183], v[204:207], v[100:103]
	v_mfma_f32_16x16x32_bf16 v[104:107], v[172:175], v[204:207], v[104:107]
	v_mfma_f32_16x16x32_bf16 v[104:107], v[176:179], v[208:211], v[104:107]
	v_mfma_f32_16x16x32_bf16 v[108:111], v[154:157], v[208:211], v[108:111]
	v_mfma_f32_16x16x32_bf16 v[108:111], v[128:131], v[204:207], v[108:111]
	v_mfma_f32_16x16x32_bf16 v[92:95], v[128:131], v[212:215], v[92:95]
	v_mfma_f32_16x16x32_bf16 v[92:95], v[154:157], v[216:219], v[92:95]
	v_mfma_f32_16x16x32_bf16 v[88:91], v[176:179], v[216:219], v[88:91]
	v_mfma_f32_16x16x32_bf16 v[88:91], v[172:175], v[212:215], v[88:91]
	v_mfma_f32_16x16x32_bf16 v[84:87], v[180:183], v[212:215], v[84:87]
	v_mfma_f32_16x16x32_bf16 v[84:87], v[184:187], v[216:219], v[84:87]
	v_mfma_f32_16x16x32_bf16 v[80:83], v[192:195], v[216:219], v[80:83]
	v_mfma_f32_16x16x32_bf16 v[80:83], v[188:191], v[212:215], v[80:83]
	v_mfma_f32_16x16x32_bf16 v[64:67], v[188:191], v[220:223], v[64:67]
	v_mfma_f32_16x16x32_bf16 v[64:67], v[192:195], v[224:227], v[64:67]
	v_mfma_f32_16x16x32_bf16 v[68:71], v[184:187], v[224:227], v[68:71]
	v_mfma_f32_16x16x32_bf16 v[68:71], v[180:183], v[220:223], v[68:71]
	v_mfma_f32_16x16x32_bf16 v[72:75], v[172:175], v[220:223], v[72:75]
	v_mfma_f32_16x16x32_bf16 v[72:75], v[176:179], v[224:227], v[72:75]
	v_mfma_f32_16x16x32_bf16 v[76:79], v[154:157], v[224:227], v[76:79]
	v_mfma_f32_16x16x32_bf16 v[76:79], v[128:131], v[220:223], v[76:79]
	s_setprio 0
	s_barrier
	s_add_i32 s20, s45, s30
	v_lshl_add_u64 v[160:161], s[24:25], 0, v[134:135]
	s_mov_b32 m0, s20
	v_lshl_add_u64 v[164:165], s[24:25], 0, v[138:139]
	global_load_lds_dwordx4 v[160:161], off
	s_add_i32 m0, s20, 0x2000
	s_add_u32 s20, s24, 0x100000
	s_addc_u32 s21, s25, 0
	s_add_i32 s55, s46, s30
	global_load_lds_dwordx4 v[164:165], off
	v_lshl_add_u64 v[196:197], s[20:21], 0, v[134:135]
	s_mov_b32 m0, s55
	v_lshl_add_u64 v[228:229], s[26:27], 0, v[132:133]
	global_load_lds_dwordx4 v[196:197], off
	v_lshl_add_u64 v[196:197], s[20:21], 0, v[138:139]
	s_add_i32 m0, s55, 0x2000
	v_lshl_add_u64 v[230:231], s[26:27], 0, v[136:137]
	global_load_lds_dwordx4 v[196:197], off
	s_mov_b32 m0, s19
	s_nop 0
	global_load_lds_dwordx4 v[228:229], off
	s_mov_b32 m0, s36
	s_nop 0
	global_load_lds_dwordx4 v[230:231], off
	ds_read_b128 v[196:199], v169 offset:16384
	ds_read_b128 v[200:203], v169 offset:17408
	ds_read_b128 v[204:207], v169 offset:18432
	ds_read_b128 v[208:211], v169 offset:19456
	ds_read_b128 v[212:215], v169 offset:20480
	ds_read_b128 v[216:219], v169 offset:21504
	ds_read_b128 v[220:223], v169 offset:22528
	ds_read_b128 v[224:227], v169 offset:23552
	s_waitcnt vmcnt(8)
	s_waitcnt lgkmcnt(0)
	s_barrier
	s_waitcnt lgkmcnt(0)
	s_setprio 1
	v_mfma_f32_16x16x32_bf16 v[60:63], v[128:131], v[196:199], v[60:63]
	v_mfma_f32_16x16x32_bf16 v[60:63], v[154:157], v[200:203], v[60:63]
	v_mfma_f32_16x16x32_bf16 v[56:59], v[176:179], v[200:203], v[56:59]
	v_mfma_f32_16x16x32_bf16 v[56:59], v[172:175], v[196:199], v[56:59]
	v_mfma_f32_16x16x32_bf16 v[52:55], v[180:183], v[196:199], v[52:55]
	v_mfma_f32_16x16x32_bf16 v[52:55], v[184:187], v[200:203], v[52:55]
	v_mfma_f32_16x16x32_bf16 v[48:51], v[192:195], v[200:203], v[48:51]
	v_mfma_f32_16x16x32_bf16 v[48:51], v[188:191], v[196:199], v[48:51]
	v_mfma_f32_16x16x32_bf16 v[32:35], v[188:191], v[204:207], v[32:35]
	v_mfma_f32_16x16x32_bf16 v[32:35], v[192:195], v[208:211], v[32:35]
	v_mfma_f32_16x16x32_bf16 v[36:39], v[184:187], v[208:211], v[36:39]
	v_mfma_f32_16x16x32_bf16 v[36:39], v[180:183], v[204:207], v[36:39]
	v_mfma_f32_16x16x32_bf16 v[40:43], v[172:175], v[204:207], v[40:43]
	v_mfma_f32_16x16x32_bf16 v[40:43], v[176:179], v[208:211], v[40:43]
	v_mfma_f32_16x16x32_bf16 v[44:47], v[154:157], v[208:211], v[44:47]
	v_mfma_f32_16x16x32_bf16 v[44:47], v[128:131], v[204:207], v[44:47]
	v_mfma_f32_16x16x32_bf16 v[28:31], v[128:131], v[212:215], v[28:31]
	v_mfma_f32_16x16x32_bf16 v[28:31], v[154:157], v[216:219], v[28:31]
	v_mfma_f32_16x16x32_bf16 v[24:27], v[176:179], v[216:219], v[24:27]
	v_mfma_f32_16x16x32_bf16 v[24:27], v[172:175], v[212:215], v[24:27]
	v_mfma_f32_16x16x32_bf16 v[20:23], v[180:183], v[212:215], v[20:23]
	v_mfma_f32_16x16x32_bf16 v[20:23], v[184:187], v[216:219], v[20:23]
	v_mfma_f32_16x16x32_bf16 v[16:19], v[192:195], v[216:219], v[16:19]
	v_mfma_f32_16x16x32_bf16 v[16:19], v[188:191], v[212:215], v[16:19]
	v_mfma_f32_16x16x32_bf16 v[0:3], v[188:191], v[220:223], v[0:3]
	v_mfma_f32_16x16x32_bf16 v[0:3], v[192:195], v[224:227], v[0:3]
	v_mfma_f32_16x16x32_bf16 v[4:7], v[184:187], v[224:227], v[4:7]
	v_mfma_f32_16x16x32_bf16 v[4:7], v[180:183], v[220:223], v[4:7]
	v_mfma_f32_16x16x32_bf16 v[8:11], v[172:175], v[220:223], v[8:11]
	v_mfma_f32_16x16x32_bf16 v[8:11], v[176:179], v[224:227], v[8:11]
	v_mfma_f32_16x16x32_bf16 v[12:15], v[154:157], v[224:227], v[12:15]
	v_mfma_f32_16x16x32_bf16 v[12:15], v[128:131], v[220:223], v[12:15]
	s_setprio 0
	s_barrier
	s_add_i32 s55, 0, 0x18000
	v_add_u32_e32 v153, s55, v159
	s_add_i32 s56, 0, 0x1c000
	ds_read_b128 v[128:131], v153
	ds_read_b128 v[154:157], v153 offset:1024
	ds_read_b128 v[172:175], v153 offset:2048
	ds_read_b128 v[176:179], v153 offset:3072
	v_add_u32_e32 v153, s56, v159
	ds_read_b128 v[180:183], v153
	ds_read_b128 v[184:187], v153 offset:1024
	ds_read_b128 v[188:191], v153 offset:2048
	ds_read_b128 v[192:195], v153 offset:3072
	s_add_u32 s20, s26, 0x100000
	s_addc_u32 s21, s27, 0
	s_mov_b32 m0, s37
	v_lshl_add_u64 v[196:197], s[20:21], 0, v[132:133]
	global_load_lds_dwordx4 v[196:197], off
	v_lshl_add_u64 v[196:197], s[20:21], 0, v[136:137]
	s_mov_b32 m0, s38
	s_nop 0
	global_load_lds_dwordx4 v[196:197], off
	ds_read_b128 v[196:199], v169 offset:32768
	ds_read_b128 v[200:203], v169 offset:33792
	ds_read_b128 v[204:207], v169 offset:34816
	ds_read_b128 v[208:211], v169 offset:35840
	ds_read_b128 v[212:215], v169 offset:36864
	ds_read_b128 v[216:219], v169 offset:37888
	ds_read_b128 v[220:223], v169 offset:38912
	ds_read_b128 v[224:227], v169 offset:39936
	s_waitcnt vmcnt(8)
	s_waitcnt lgkmcnt(0)
	s_barrier
	s_waitcnt lgkmcnt(0)
	s_setprio 1
	v_mfma_f32_16x16x32_bf16 v[124:127], v[128:131], v[196:199], v[124:127]
	v_mfma_f32_16x16x32_bf16 v[124:127], v[154:157], v[200:203], v[124:127]
	v_mfma_f32_16x16x32_bf16 v[120:123], v[176:179], v[200:203], v[120:123]
	v_mfma_f32_16x16x32_bf16 v[120:123], v[172:175], v[196:199], v[120:123]
	v_mfma_f32_16x16x32_bf16 v[116:119], v[180:183], v[196:199], v[116:119]
	v_mfma_f32_16x16x32_bf16 v[116:119], v[184:187], v[200:203], v[116:119]
	v_mfma_f32_16x16x32_bf16 v[112:115], v[192:195], v[200:203], v[112:115]
	v_mfma_f32_16x16x32_bf16 v[112:115], v[188:191], v[196:199], v[112:115]
	v_mfma_f32_16x16x32_bf16 v[96:99], v[188:191], v[204:207], v[96:99]
	v_mfma_f32_16x16x32_bf16 v[96:99], v[192:195], v[208:211], v[96:99]
	v_mfma_f32_16x16x32_bf16 v[100:103], v[184:187], v[208:211], v[100:103]
	v_mfma_f32_16x16x32_bf16 v[100:103], v[180:183], v[204:207], v[100:103]
	v_mfma_f32_16x16x32_bf16 v[104:107], v[172:175], v[204:207], v[104:107]
	v_mfma_f32_16x16x32_bf16 v[104:107], v[176:179], v[208:211], v[104:107]
	v_mfma_f32_16x16x32_bf16 v[108:111], v[154:157], v[208:211], v[108:111]
	v_mfma_f32_16x16x32_bf16 v[108:111], v[128:131], v[204:207], v[108:111]
	v_mfma_f32_16x16x32_bf16 v[92:95], v[128:131], v[212:215], v[92:95]
	v_mfma_f32_16x16x32_bf16 v[92:95], v[154:157], v[216:219], v[92:95]
	v_mfma_f32_16x16x32_bf16 v[88:91], v[176:179], v[216:219], v[88:91]
	v_mfma_f32_16x16x32_bf16 v[88:91], v[172:175], v[212:215], v[88:91]
	v_mfma_f32_16x16x32_bf16 v[84:87], v[180:183], v[212:215], v[84:87]
	v_mfma_f32_16x16x32_bf16 v[84:87], v[184:187], v[216:219], v[84:87]
	v_mfma_f32_16x16x32_bf16 v[80:83], v[192:195], v[216:219], v[80:83]
	v_mfma_f32_16x16x32_bf16 v[80:83], v[188:191], v[212:215], v[80:83]
	v_mfma_f32_16x16x32_bf16 v[64:67], v[188:191], v[220:223], v[64:67]
	v_mfma_f32_16x16x32_bf16 v[64:67], v[192:195], v[224:227], v[64:67]
	v_mfma_f32_16x16x32_bf16 v[68:71], v[184:187], v[224:227], v[68:71]
	v_mfma_f32_16x16x32_bf16 v[68:71], v[180:183], v[220:223], v[68:71]
	v_mfma_f32_16x16x32_bf16 v[72:75], v[172:175], v[220:223], v[72:75]
	v_mfma_f32_16x16x32_bf16 v[72:75], v[176:179], v[224:227], v[72:75]
	v_mfma_f32_16x16x32_bf16 v[76:79], v[154:157], v[224:227], v[76:79]
	v_mfma_f32_16x16x32_bf16 v[76:79], v[128:131], v[220:223], v[76:79]
	s_setprio 0
	s_barrier
	s_add_i32 s20, s55, s30
	v_lshl_add_u64 v[160:161], v[160:161], 0, s[8:9]
	s_mov_b32 m0, s20
	s_nop 0
	global_load_lds_dwordx4 v[160:161], off
	s_add_i32 m0, s20, 0x2000
	s_add_u32 s20, s24, 0x100800
	v_lshl_add_u64 v[160:161], v[164:165], 0, s[8:9]
	s_addc_u32 s21, s25, 0
	s_add_i32 s24, s56, s30
	global_load_lds_dwordx4 v[160:161], off
	v_lshl_add_u64 v[160:161], s[20:21], 0, v[134:135]
	s_mov_b32 m0, s24
	s_nop 0
	global_load_lds_dwordx4 v[160:161], off
	v_lshl_add_u64 v[160:161], s[20:21], 0, v[138:139]
	s_add_i32 m0, s24, 0x2000
	s_nop 0
	global_load_lds_dwordx4 v[160:161], off
	v_lshl_add_u64 v[160:161], v[228:229], 0, s[8:9]
	s_mov_b32 m0, s41
	s_nop 0
	global_load_lds_dwordx4 v[160:161], off
	v_lshl_add_u64 v[160:161], v[230:231], 0, s[8:9]
	s_mov_b32 m0, s42
	s_nop 0
	global_load_lds_dwordx4 v[160:161], off
	ds_read_b128 v[196:199], v169 offset:49152
	ds_read_b128 v[200:203], v169 offset:50176
	ds_read_b128 v[204:207], v169 offset:51200
	ds_read_b128 v[208:211], v169 offset:52224
	ds_read_b128 v[212:215], v169 offset:53248
	ds_read_b128 v[216:219], v169 offset:54272
	ds_read_b128 v[220:223], v169 offset:55296
	ds_read_b128 v[224:227], v169 offset:56320
	s_waitcnt vmcnt(8)
	s_waitcnt lgkmcnt(0)
	s_barrier
	s_waitcnt lgkmcnt(0)
	s_setprio 1
	v_mfma_f32_16x16x32_bf16 v[60:63], v[128:131], v[196:199], v[60:63]
	v_mfma_f32_16x16x32_bf16 v[60:63], v[154:157], v[200:203], v[60:63]
	v_mfma_f32_16x16x32_bf16 v[56:59], v[176:179], v[200:203], v[56:59]
	v_mfma_f32_16x16x32_bf16 v[56:59], v[172:175], v[196:199], v[56:59]
	v_mfma_f32_16x16x32_bf16 v[52:55], v[180:183], v[196:199], v[52:55]
	v_mfma_f32_16x16x32_bf16 v[52:55], v[184:187], v[200:203], v[52:55]
	v_mfma_f32_16x16x32_bf16 v[48:51], v[192:195], v[200:203], v[48:51]
	v_mfma_f32_16x16x32_bf16 v[48:51], v[188:191], v[196:199], v[48:51]
	v_mfma_f32_16x16x32_bf16 v[32:35], v[188:191], v[204:207], v[32:35]
	v_mfma_f32_16x16x32_bf16 v[32:35], v[192:195], v[208:211], v[32:35]
	v_mfma_f32_16x16x32_bf16 v[36:39], v[184:187], v[208:211], v[36:39]
	v_mfma_f32_16x16x32_bf16 v[36:39], v[180:183], v[204:207], v[36:39]
	v_mfma_f32_16x16x32_bf16 v[40:43], v[172:175], v[204:207], v[40:43]
	v_mfma_f32_16x16x32_bf16 v[40:43], v[176:179], v[208:211], v[40:43]
	v_mfma_f32_16x16x32_bf16 v[44:47], v[154:157], v[208:211], v[44:47]
	v_mfma_f32_16x16x32_bf16 v[44:47], v[128:131], v[204:207], v[44:47]
	v_mfma_f32_16x16x32_bf16 v[28:31], v[128:131], v[212:215], v[28:31]
	v_mfma_f32_16x16x32_bf16 v[28:31], v[154:157], v[216:219], v[28:31]
	v_mfma_f32_16x16x32_bf16 v[24:27], v[176:179], v[216:219], v[24:27]
	v_mfma_f32_16x16x32_bf16 v[24:27], v[172:175], v[212:215], v[24:27]
	v_mfma_f32_16x16x32_bf16 v[20:23], v[180:183], v[212:215], v[20:23]
	v_mfma_f32_16x16x32_bf16 v[20:23], v[184:187], v[216:219], v[20:23]
	v_mfma_f32_16x16x32_bf16 v[16:19], v[192:195], v[216:219], v[16:19]
	v_mfma_f32_16x16x32_bf16 v[16:19], v[188:191], v[212:215], v[16:19]
	v_mfma_f32_16x16x32_bf16 v[0:3], v[188:191], v[220:223], v[0:3]
	v_mfma_f32_16x16x32_bf16 v[0:3], v[192:195], v[224:227], v[0:3]
	v_mfma_f32_16x16x32_bf16 v[4:7], v[184:187], v[224:227], v[4:7]
	v_mfma_f32_16x16x32_bf16 v[4:7], v[180:183], v[220:223], v[4:7]
	v_mfma_f32_16x16x32_bf16 v[8:11], v[172:175], v[220:223], v[8:11]
	v_mfma_f32_16x16x32_bf16 v[8:11], v[176:179], v[224:227], v[8:11]
	v_mfma_f32_16x16x32_bf16 v[12:15], v[154:157], v[224:227], v[12:15]
	v_mfma_f32_16x16x32_bf16 v[12:15], v[128:131], v[220:223], v[12:15]
	s_setprio 0
	s_barrier
	s_add_i32 s54, s54, 2
	s_add_u32 s52, s52, 0x1000
	s_addc_u32 s53, s53, 0
	s_cmp_gt_u32 s54, 61
	s_mov_b64 s[20:21], s[22:23]
	s_cbranch_scc0 .LBB0_1543
	s_and_b64 vcc, exec, s[4:5]
	s_cbranch_vccz .LBB0_1546
	s_barrier

.LBB0_1625:
	ds_read_b128 v[128:131], v177
	ds_read_b128 v[132:135], v177 offset:1024
	ds_read_b128 v[136:139], v177 offset:2048
	ds_read_b128 v[140:143], v177 offset:3072
	ds_read_b128 v[144:147], v178
	ds_read_b128 v[148:151], v178 offset:1024
	ds_read_b128 v[170:173], v178 offset:2048
	ds_read_b128 v[182:185], v178 offset:3072
	s_add_u32 s24, s22, 0xffc00800
	s_addc_u32 s25, s23, -1
	s_cmpk_eq_i32 s57, 0xfc
	s_cselect_b32 s27, s29, s25
	s_cselect_b32 s26, s53, s24
	s_cselect_b32 s25, s17, s56
	s_cselect_b32 s24, s54, s55
	v_lshl_add_u64 v[186:187], s[22:23], 0, v[162:163]
	s_add_i32 m0, s38, 0xc000
	s_nop 0
	global_load_lds_dwordx4 v[186:187], off
	v_lshl_add_u64 v[186:187], s[22:23], 0, v[164:165]
	s_add_i32 m0, s38, 0xe000
	s_nop 0
	global_load_lds_dwordx4 v[186:187], off
	ds_read_b128 v[186:189], v179
	ds_read_b128 v[190:193], v179 offset:1024
	ds_read_b128 v[194:197], v179 offset:2048
	ds_read_b128 v[198:201], v179 offset:3072
	ds_read_b128 v[202:205], v179 offset:4096
	ds_read_b128 v[206:209], v179 offset:5120
	ds_read_b128 v[210:213], v179 offset:6144
	ds_read_b128 v[214:217], v179 offset:7168
	s_waitcnt vmcnt(8)
	s_waitcnt lgkmcnt(0)
	s_barrier
	s_waitcnt lgkmcnt(0)
	s_setprio 1
	v_mfma_f32_16x16x32_bf16 v[124:127], v[128:131], v[186:189], v[124:127]
	v_mfma_f32_16x16x32_bf16 v[124:127], v[132:135], v[190:193], v[124:127]
	v_mfma_f32_16x16x32_bf16 v[120:123], v[140:143], v[190:193], v[120:123]
	v_mfma_f32_16x16x32_bf16 v[120:123], v[136:139], v[186:189], v[120:123]
	v_mfma_f32_16x16x32_bf16 v[116:119], v[144:147], v[186:189], v[116:119]
	v_mfma_f32_16x16x32_bf16 v[116:119], v[148:151], v[190:193], v[116:119]
	v_mfma_f32_16x16x32_bf16 v[112:115], v[182:185], v[190:193], v[112:115]
	v_mfma_f32_16x16x32_bf16 v[112:115], v[170:173], v[186:189], v[112:115]
	v_mfma_f32_16x16x32_bf16 v[96:99], v[170:173], v[194:197], v[96:99]
	v_mfma_f32_16x16x32_bf16 v[96:99], v[182:185], v[198:201], v[96:99]
	v_mfma_f32_16x16x32_bf16 v[100:103], v[148:151], v[198:201], v[100:103]
	v_mfma_f32_16x16x32_bf16 v[100:103], v[144:147], v[194:197], v[100:103]
	v_mfma_f32_16x16x32_bf16 v[104:107], v[136:139], v[194:197], v[104:107]
	v_mfma_f32_16x16x32_bf16 v[104:107], v[140:143], v[198:201], v[104:107]
	v_mfma_f32_16x16x32_bf16 v[108:111], v[132:135], v[198:201], v[108:111]
	v_mfma_f32_16x16x32_bf16 v[108:111], v[128:131], v[194:197], v[108:111]
	v_mfma_f32_16x16x32_bf16 v[92:95], v[128:131], v[202:205], v[92:95]
	v_mfma_f32_16x16x32_bf16 v[92:95], v[132:135], v[206:209], v[92:95]
	v_mfma_f32_16x16x32_bf16 v[88:91], v[140:143], v[206:209], v[88:91]
	v_mfma_f32_16x16x32_bf16 v[88:91], v[136:139], v[202:205], v[88:91]
	v_mfma_f32_16x16x32_bf16 v[84:87], v[144:147], v[202:205], v[84:87]
	v_mfma_f32_16x16x32_bf16 v[84:87], v[148:151], v[206:209], v[84:87]
	v_mfma_f32_16x16x32_bf16 v[80:83], v[182:185], v[206:209], v[80:83]
	v_mfma_f32_16x16x32_bf16 v[80:83], v[170:173], v[202:205], v[80:83]
	v_mfma_f32_16x16x32_bf16 v[64:67], v[170:173], v[210:213], v[64:67]
	v_mfma_f32_16x16x32_bf16 v[64:67], v[182:185], v[214:217], v[64:67]
	v_mfma_f32_16x16x32_bf16 v[68:71], v[148:151], v[214:217], v[68:71]
	v_mfma_f32_16x16x32_bf16 v[68:71], v[144:147], v[210:213], v[68:71]
	v_mfma_f32_16x16x32_bf16 v[72:75], v[136:139], v[210:213], v[72:75]
	v_mfma_f32_16x16x32_bf16 v[72:75], v[140:143], v[214:217], v[72:75]
	v_mfma_f32_16x16x32_bf16 v[76:79], v[132:135], v[214:217], v[76:79]
	v_mfma_f32_16x16x32_bf16 v[76:79], v[128:131], v[210:213], v[76:79]
	s_setprio 0
	s_barrier
	s_add_i32 s58, s48, s37
	v_lshl_add_u64 v[218:219], s[24:25], 0, v[154:155]
	s_mov_b32 m0, s58
	v_lshl_add_u64 v[220:221], s[24:25], 0, v[158:159]
	global_load_lds_dwordx4 v[218:219], off
	s_add_i32 m0, s58, 0x2000
	s_add_u32 s58, s24, 0x400000
	s_addc_u32 s59, s25, 0
	s_add_i32 s60, s49, s37
	global_load_lds_dwordx4 v[220:221], off
	v_lshl_add_u64 v[186:187], s[58:59], 0, v[154:155]
	s_mov_b32 m0, s60
	v_lshl_add_u64 v[222:223], s[26:27], 0, v[152:153]
	global_load_lds_dwordx4 v[186:187], off
	v_lshl_add_u64 v[186:187], s[58:59], 0, v[158:159]
	s_add_i32 m0, s60, 0x2000
	v_lshl_add_u64 v[224:225], s[26:27], 0, v[156:157]
	global_load_lds_dwordx4 v[186:187], off
	s_mov_b32 m0, s38
	s_nop 0
	global_load_lds_dwordx4 v[222:223], off
	s_mov_b32 m0, s39
	s_nop 0
	global_load_lds_dwordx4 v[224:225], off
	ds_read_b128 v[186:189], v179 offset:16384
	ds_read_b128 v[190:193], v179 offset:17408
	ds_read_b128 v[194:197], v179 offset:18432
	ds_read_b128 v[198:201], v179 offset:19456
	ds_read_b128 v[202:205], v179 offset:20480
	ds_read_b128 v[206:209], v179 offset:21504
	ds_read_b128 v[210:213], v179 offset:22528
	ds_read_b128 v[214:217], v179 offset:23552
	s_waitcnt vmcnt(8)
	s_waitcnt lgkmcnt(0)
	s_barrier
	s_waitcnt lgkmcnt(0)
	s_setprio 1
	v_mfma_f32_16x16x32_bf16 v[60:63], v[128:131], v[186:189], v[60:63]
	v_mfma_f32_16x16x32_bf16 v[60:63], v[132:135], v[190:193], v[60:63]
	v_mfma_f32_16x16x32_bf16 v[56:59], v[140:143], v[190:193], v[56:59]
	v_mfma_f32_16x16x32_bf16 v[56:59], v[136:139], v[186:189], v[56:59]
	v_mfma_f32_16x16x32_bf16 v[52:55], v[144:147], v[186:189], v[52:55]
	v_mfma_f32_16x16x32_bf16 v[52:55], v[148:151], v[190:193], v[52:55]
	v_mfma_f32_16x16x32_bf16 v[48:51], v[182:185], v[190:193], v[48:51]
	v_mfma_f32_16x16x32_bf16 v[48:51], v[170:173], v[186:189], v[48:51]
	v_mfma_f32_16x16x32_bf16 v[32:35], v[170:173], v[194:197], v[32:35]
	v_mfma_f32_16x16x32_bf16 v[32:35], v[182:185], v[198:201], v[32:35]
	v_mfma_f32_16x16x32_bf16 v[36:39], v[148:151], v[198:201], v[36:39]
	v_mfma_f32_16x16x32_bf16 v[36:39], v[144:147], v[194:197], v[36:39]
	v_mfma_f32_16x16x32_bf16 v[40:43], v[136:139], v[194:197], v[40:43]
	v_mfma_f32_16x16x32_bf16 v[40:43], v[140:143], v[198:201], v[40:43]
	v_mfma_f32_16x16x32_bf16 v[44:47], v[132:135], v[198:201], v[44:47]
	v_mfma_f32_16x16x32_bf16 v[44:47], v[128:131], v[194:197], v[44:47]
	v_mfma_f32_16x16x32_bf16 v[28:31], v[128:131], v[202:205], v[28:31]
	v_mfma_f32_16x16x32_bf16 v[28:31], v[132:135], v[206:209], v[28:31]
	v_mfma_f32_16x16x32_bf16 v[24:27], v[140:143], v[206:209], v[24:27]
	v_mfma_f32_16x16x32_bf16 v[24:27], v[136:139], v[202:205], v[24:27]
	v_mfma_f32_16x16x32_bf16 v[20:23], v[144:147], v[202:205], v[20:23]
	v_mfma_f32_16x16x32_bf16 v[20:23], v[148:151], v[206:209], v[20:23]
	v_mfma_f32_16x16x32_bf16 v[16:19], v[182:185], v[206:209], v[16:19]
	v_mfma_f32_16x16x32_bf16 v[16:19], v[170:173], v[202:205], v[16:19]
	v_mfma_f32_16x16x32_bf16 v[0:3], v[170:173], v[210:213], v[0:3]
	v_mfma_f32_16x16x32_bf16 v[0:3], v[182:185], v[214:217], v[0:3]
	v_mfma_f32_16x16x32_bf16 v[4:7], v[148:151], v[214:217], v[4:7]
	v_mfma_f32_16x16x32_bf16 v[4:7], v[144:147], v[210:213], v[4:7]
	v_mfma_f32_16x16x32_bf16 v[8:11], v[136:139], v[210:213], v[8:11]
	v_mfma_f32_16x16x32_bf16 v[8:11], v[140:143], v[214:217], v[8:11]
	v_mfma_f32_16x16x32_bf16 v[12:15], v[132:135], v[214:217], v[12:15]
	v_mfma_f32_16x16x32_bf16 v[12:15], v[128:131], v[210:213], v[12:15]
	s_setprio 0
	s_barrier
	s_add_i32 s58, 0, 0x18000
	s_add_i32 s59, 0, 0x1c000
	v_add_u32_e32 v140, s58, v174
	v_add_u32_e32 v181, s59, v174
	ds_read_b128 v[128:131], v140
	ds_read_b128 v[132:135], v140 offset:1024
	ds_read_b128 v[136:139], v140 offset:2048
	ds_read_b128 v[140:143], v140 offset:3072
	ds_read_b128 v[144:147], v181
	ds_read_b128 v[148:151], v181 offset:1024
	ds_read_b128 v[170:173], v181 offset:2048
	ds_read_b128 v[182:185], v181 offset:3072
	s_add_u32 s26, s26, 0x400000
	s_addc_u32 s27, s27, 0
	s_mov_b32 m0, s40
	v_lshl_add_u64 v[186:187], s[26:27], 0, v[152:153]
	global_load_lds_dwordx4 v[186:187], off
	v_lshl_add_u64 v[186:187], s[26:27], 0, v[156:157]
	s_mov_b32 m0, s41
	s_nop 0
	global_load_lds_dwordx4 v[186:187], off
	ds_read_b128 v[186:189], v179 offset:32768
	ds_read_b128 v[190:193], v179 offset:33792
	ds_read_b128 v[194:197], v179 offset:34816
	ds_read_b128 v[198:201], v179 offset:35840
	ds_read_b128 v[202:205], v179 offset:36864
	ds_read_b128 v[206:209], v179 offset:37888
	ds_read_b128 v[210:213], v179 offset:38912
	ds_read_b128 v[214:217], v179 offset:39936
	s_waitcnt vmcnt(8)
	s_waitcnt lgkmcnt(0)
	s_barrier
	s_waitcnt lgkmcnt(0)
	s_setprio 1
	v_mfma_f32_16x16x32_bf16 v[124:127], v[128:131], v[186:189], v[124:127]
	v_mfma_f32_16x16x32_bf16 v[124:127], v[132:135], v[190:193], v[124:127]
	v_mfma_f32_16x16x32_bf16 v[120:123], v[140:143], v[190:193], v[120:123]
	v_mfma_f32_16x16x32_bf16 v[120:123], v[136:139], v[186:189], v[120:123]
	v_mfma_f32_16x16x32_bf16 v[116:119], v[144:147], v[186:189], v[116:119]
	v_mfma_f32_16x16x32_bf16 v[116:119], v[148:151], v[190:193], v[116:119]
	v_mfma_f32_16x16x32_bf16 v[112:115], v[182:185], v[190:193], v[112:115]
	v_mfma_f32_16x16x32_bf16 v[112:115], v[170:173], v[186:189], v[112:115]
	v_mfma_f32_16x16x32_bf16 v[96:99], v[170:173], v[194:197], v[96:99]
	v_mfma_f32_16x16x32_bf16 v[96:99], v[182:185], v[198:201], v[96:99]
	v_mfma_f32_16x16x32_bf16 v[100:103], v[148:151], v[198:201], v[100:103]
	v_mfma_f32_16x16x32_bf16 v[100:103], v[144:147], v[194:197], v[100:103]
	v_mfma_f32_16x16x32_bf16 v[104:107], v[136:139], v[194:197], v[104:107]
	v_mfma_f32_16x16x32_bf16 v[104:107], v[140:143], v[198:201], v[104:107]
	v_mfma_f32_16x16x32_bf16 v[108:111], v[132:135], v[198:201], v[108:111]
	v_mfma_f32_16x16x32_bf16 v[108:111], v[128:131], v[194:197], v[108:111]
	v_mfma_f32_16x16x32_bf16 v[92:95], v[128:131], v[202:205], v[92:95]
	v_mfma_f32_16x16x32_bf16 v[92:95], v[132:135], v[206:209], v[92:95]
	v_mfma_f32_16x16x32_bf16 v[88:91], v[140:143], v[206:209], v[88:91]
	v_mfma_f32_16x16x32_bf16 v[88:91], v[136:139], v[202:205], v[88:91]
	v_mfma_f32_16x16x32_bf16 v[84:87], v[144:147], v[202:205], v[84:87]
	v_mfma_f32_16x16x32_bf16 v[84:87], v[148:151], v[206:209], v[84:87]
	v_mfma_f32_16x16x32_bf16 v[80:83], v[182:185], v[206:209], v[80:83]
	v_mfma_f32_16x16x32_bf16 v[80:83], v[170:173], v[202:205], v[80:83]
	v_mfma_f32_16x16x32_bf16 v[64:67], v[170:173], v[210:213], v[64:67]
	v_mfma_f32_16x16x32_bf16 v[64:67], v[182:185], v[214:217], v[64:67]
	v_mfma_f32_16x16x32_bf16 v[68:71], v[148:151], v[214:217], v[68:71]
	v_mfma_f32_16x16x32_bf16 v[68:71], v[144:147], v[210:213], v[68:71]
	v_mfma_f32_16x16x32_bf16 v[72:75], v[136:139], v[210:213], v[72:75]
	v_mfma_f32_16x16x32_bf16 v[72:75], v[140:143], v[214:217], v[72:75]
	v_mfma_f32_16x16x32_bf16 v[76:79], v[132:135], v[214:217], v[76:79]
	v_mfma_f32_16x16x32_bf16 v[76:79], v[128:131], v[210:213], v[76:79]
	s_setprio 0
	s_barrier
	s_add_i32 s26, s58, s37
	v_lshl_add_u64 v[186:187], v[218:219], 0, s[14:15]
	s_mov_b32 m0, s26
	s_nop 0
	global_load_lds_dwordx4 v[186:187], off
	s_add_i32 m0, s26, 0x2000
	s_add_u32 s24, s24, 0x400800
	v_lshl_add_u64 v[186:187], v[220:221], 0, s[14:15]
	s_addc_u32 s25, s25, 0
	s_add_i32 s26, s59, s37
	global_load_lds_dwordx4 v[186:187], off
	v_lshl_add_u64 v[186:187], s[24:25], 0, v[154:155]
	s_mov_b32 m0, s26
	s_nop 0
	global_load_lds_dwordx4 v[186:187], off
	v_lshl_add_u64 v[186:187], s[24:25], 0, v[158:159]
	s_add_i32 m0, s26, 0x2000
	s_nop 0
	global_load_lds_dwordx4 v[186:187], off
	v_lshl_add_u64 v[186:187], v[222:223], 0, s[14:15]
	s_mov_b32 m0, s43
	s_nop 0
	global_load_lds_dwordx4 v[186:187], off
	v_lshl_add_u64 v[186:187], v[224:225], 0, s[14:15]
	s_mov_b32 m0, s44
	s_nop 0
	global_load_lds_dwordx4 v[186:187], off
	ds_read_b128 v[186:189], v179 offset:49152
	ds_read_b128 v[190:193], v179 offset:50176
	ds_read_b128 v[194:197], v179 offset:51200
	ds_read_b128 v[198:201], v179 offset:52224
	ds_read_b128 v[202:205], v179 offset:53248
	ds_read_b128 v[206:209], v179 offset:54272
	ds_read_b128 v[210:213], v179 offset:55296
	ds_read_b128 v[214:217], v179 offset:56320
	s_waitcnt vmcnt(8)
	s_waitcnt lgkmcnt(0)
	s_barrier
	s_waitcnt lgkmcnt(0)
	s_setprio 1
	v_mfma_f32_16x16x32_bf16 v[60:63], v[128:131], v[186:189], v[60:63]
	v_mfma_f32_16x16x32_bf16 v[60:63], v[132:135], v[190:193], v[60:63]
	v_mfma_f32_16x16x32_bf16 v[56:59], v[140:143], v[190:193], v[56:59]
	v_mfma_f32_16x16x32_bf16 v[56:59], v[136:139], v[186:189], v[56:59]
	v_mfma_f32_16x16x32_bf16 v[52:55], v[144:147], v[186:189], v[52:55]
	v_mfma_f32_16x16x32_bf16 v[52:55], v[148:151], v[190:193], v[52:55]
	v_mfma_f32_16x16x32_bf16 v[48:51], v[182:185], v[190:193], v[48:51]
	v_mfma_f32_16x16x32_bf16 v[48:51], v[170:173], v[186:189], v[48:51]
	v_mfma_f32_16x16x32_bf16 v[32:35], v[170:173], v[194:197], v[32:35]
	v_mfma_f32_16x16x32_bf16 v[32:35], v[182:185], v[198:201], v[32:35]
	v_mfma_f32_16x16x32_bf16 v[36:39], v[148:151], v[198:201], v[36:39]
	v_mfma_f32_16x16x32_bf16 v[36:39], v[144:147], v[194:197], v[36:39]
	v_mfma_f32_16x16x32_bf16 v[40:43], v[136:139], v[194:197], v[40:43]
	v_mfma_f32_16x16x32_bf16 v[40:43], v[140:143], v[198:201], v[40:43]
	v_mfma_f32_16x16x32_bf16 v[44:47], v[132:135], v[198:201], v[44:47]
	v_mfma_f32_16x16x32_bf16 v[44:47], v[128:131], v[194:197], v[44:47]
	v_mfma_f32_16x16x32_bf16 v[28:31], v[128:131], v[202:205], v[28:31]
	v_mfma_f32_16x16x32_bf16 v[28:31], v[132:135], v[206:209], v[28:31]
	v_mfma_f32_16x16x32_bf16 v[24:27], v[140:143], v[206:209], v[24:27]
	v_mfma_f32_16x16x32_bf16 v[24:27], v[136:139], v[202:205], v[24:27]
	v_mfma_f32_16x16x32_bf16 v[20:23], v[144:147], v[202:205], v[20:23]
	v_mfma_f32_16x16x32_bf16 v[20:23], v[148:151], v[206:209], v[20:23]
	v_mfma_f32_16x16x32_bf16 v[16:19], v[182:185], v[206:209], v[16:19]
	v_mfma_f32_16x16x32_bf16 v[16:19], v[170:173], v[202:205], v[16:19]
	v_mfma_f32_16x16x32_bf16 v[0:3], v[170:173], v[210:213], v[0:3]
	v_mfma_f32_16x16x32_bf16 v[0:3], v[182:185], v[214:217], v[0:3]
	v_mfma_f32_16x16x32_bf16 v[4:7], v[148:151], v[214:217], v[4:7]
	v_mfma_f32_16x16x32_bf16 v[4:7], v[144:147], v[210:213], v[4:7]
	v_mfma_f32_16x16x32_bf16 v[8:11], v[136:139], v[210:213], v[8:11]
	v_mfma_f32_16x16x32_bf16 v[8:11], v[140:143], v[214:217], v[8:11]
	v_mfma_f32_16x16x32_bf16 v[12:15], v[132:135], v[214:217], v[12:15]
	v_mfma_f32_16x16x32_bf16 v[12:15], v[128:131], v[210:213], v[12:15]
	s_setprio 0
	s_barrier
	s_add_i32 s57, s57, 2
	s_add_u32 s22, s22, 0x1000
	s_addc_u32 s23, s23, 0
	s_add_u32 s55, s55, 0x1000
	s_addc_u32 s56, s56, 0
	s_cmpk_gt_u32 s57, 0xfd
	s_cbranch_scc0 .LBB0_1625
	s_and_b64 vcc, exec, s[6:7]
	s_cbranch_vccz .LBB0_1628
	s_barrier
